# nt hint on the SSD-out phase's last-use load streams (z, scanned states, conv inputs) on top of the P0 nt version
# speedup vs baseline: 1.0003x; 1.0003x over previous
;     __device__ __forceinline__ int lane_() const { return hw_lane(); }
; __device__ __forceinline__ void vec_load(Frame& F, const Ptrs& P, int b, int c, int h0, float& v0, float& v1) {
;     const float* DT = (const float*)(P.ws + WS_DT);
;     const int lane = F.lane_(), hl = F.wave >> 1, dir = F.wave & 1, h = h0 + hl;
;     const size_t row0 = (size_t)b * SEQ + c * 128;
;     v0 = DT[(row0 + lane) * 32 + dir * 16 + h]; v1 = DT[(row0 + 64 + lane) * 32 + dir * 16 + h];
; }
; __device__ __forceinline__ void vec_compute(Frame& F, const Ptrs& P, int b, int c, int h0, float v0, float v1, float* DEC) {
;     const int lane = F.lane_(), hl = F.wave >> 1, dir = F.wave & 1, h = h0 + hl;
;     const float A2 = -expf(dir ? P.alb[h] : P.alf[h]) * LOG2E;
; template <class Wait>
; __device__ __forceinline__ void out_unit(Frame& F, const Ptrs& P, int b, int c, int g, const Wait& wait) {
;     ...
;     float dv0, dv1; vec_load(F, P, b, c, h0, dv0, dv1);
;     ConvRaw R2;
;     conv_load(R2, XBC, b, c, col2, rg2);
;     { const unsigned char* blk = SB + ((((size_t)b * 64 + c) * 2 + 0) * 16 + h) * 16384 + hi * 512 + r32 * 16;
; #pragma unroll
;       for (int pb = 0; pb < 2; ++pb)
; #pragma unroll
;           for (int ks = 0; ks < 8; ++ks) A0[pb][ks] = *(const bf16x8*)(blk + (pb * 8 + ks) * 1024); }
;     vec_compute(F, P, b, c, h0, dv0, dv1, nullptr);
.LBB0_713:
	v_mbcnt_lo_u32_b32 v0, -1, 0
	v_mbcnt_hi_u32_b32 v0, -1, v0
	s_xor_b64 s[52:53], s[0:1], -1
	v_add_u32_e32 v224, s60, v0
	s_or_b32 s0, s2, s12
	v_ashrrev_i32_e32 v142, 7, v224
	v_and_b32_e32 v140, 7, v224
	v_bfe_u32 v141, v224, 3, 4
	v_add_u32_e32 v0, s0, v142
	s_waitcnt lgkmcnt(0)
	v_lshlrev_b32_e32 v1, 3, v140
	v_and_b32_e32 v222, 31, v224
	v_bfe_u32 v223, v224, 5, 1
	v_lshl_or_b32 v130, v0, 6, v1
	v_lshlrev_b32_e32 v0, 3, v141
	s_add_i32 s18, s0, s63
	s_and_b64 vcc, exec, s[52:53]
	v_ashrrev_i32_e32 v131, 31, v130
	v_lshlrev_b32_e32 v200, 9, v223
	v_lshlrev_b32_e32 v128, 4, v222
	v_add_u32_e32 v143, s64, v0
	v_or_b32_e32 v144, s13, v0
	s_mov_b64 s[0:1], -1
	s_cbranch_vccz .LBB0_719
	v_mbcnt_lo_u32_b32 v0, -1, 0
	v_mbcnt_hi_u32_b32 v0, -1, v0
	s_lshl_b64 s[0:1], s[18:19], 2
	v_ashrrev_i32_e32 v1, 31, v0
	v_lshl_add_u64 v[2:3], s[44:45], 0, v[0:1]
	v_lshlrev_b64 v[2:3], 7, v[2:3]
	v_lshl_add_u64 v[0:1], s[46:47], 0, v[0:1]
	v_lshl_add_u64 v[2:3], s[22:23], 0, v[2:3]
	v_lshlrev_b64 v[0:1], 7, v[0:1]
	v_lshl_add_u64 v[2:3], v[2:3], 0, s[0:1]
	v_lshl_add_u64 v[0:1], s[22:23], 0, v[0:1]
	v_lshl_add_u64 v[0:1], v[0:1], 0, s[0:1]
	global_load_dword v25, v[2:3], off nt
	global_load_dword v28, v[0:1], off nt
	s_add_u32 s98, s85, s0
	s_addc_u32 s99, s84, s1
	global_load_dword v24, v201, s[98:99] nt
	v_lshlrev_b64 v[190:191], 2, v[130:131]
	v_lshl_add_u64 v[192:193], s[24:25], 0, v[190:191]
	global_load_dwordx4 v[158:161], v[192:193], off offset:16 nt
	global_load_dwordx4 v[162:165], v[192:193], off nt
	v_lshl_add_u64 v[192:193], s[30:31], 0, v[190:191]
	global_load_dwordx4 v[166:169], v[192:193], off offset:16 nt
	global_load_dwordx4 v[170:173], v[192:193], off nt
	v_lshl_add_u64 v[192:193], s[36:37], 0, v[190:191]
	global_load_dwordx4 v[174:177], v[192:193], off offset:16 nt
	global_load_dwordx4 v[178:181], v[192:193], off nt
	v_lshl_add_u64 v[192:193], s[26:27], 0, v[190:191]
	global_load_dwordx4 v[182:185], v[192:193], off offset:16 nt
	global_load_dwordx4 v[186:189], v[192:193], off nt
	v_max_i32_e32 v2, 0, v143
	v_mov_b32_e32 v3, v201
	v_lshl_add_u64 v[0:1], v[130:131], 1, s[14:15]
	v_lshl_add_u64 v[2:3], s[42:43], 0, v[2:3]
	v_mad_u64_u32 v[4:5], s[2:3], v2, s87, v[0:1]
	v_or_b32_e32 v2, s42, v144
	v_mad_i32_i24 v5, v3, s87, v5
	v_mad_u64_u32 v[2:3], s[2:3], v2, s87, v[0:1]
	v_mad_i32_i24 v3, s43, v203, v3
	global_load_dwordx4 v[12:15], v[4:5], off nt
	global_load_dwordx4 v[120:123], v[2:3], off nt
	v_add_u32_e32 v2, 2, v143
	v_mov_b32_e32 v3, v201
	v_lshl_add_u64 v[2:3], s[42:43], 0, v[2:3]
	v_mad_u64_u32 v[4:5], s[2:3], v2, s87, v[0:1]
	v_mad_i32_i24 v5, v3, s87, v5
	v_add_u32_e32 v2, 3, v143
	v_mov_b32_e32 v3, v201
	v_lshl_add_u64 v[2:3], s[42:43], 0, v[2:3]
	v_mad_u64_u32 v[6:7], s[2:3], v2, s87, v[0:1]
	v_mad_i32_i24 v7, v3, s87, v7
	v_add_u32_e32 v2, 4, v143
	v_mov_b32_e32 v3, v201
	v_lshl_add_u64 v[2:3], s[42:43], 0, v[2:3]
	global_load_dwordx4 v[124:127], v[4:5], off nt
	global_load_dwordx4 v[60:63], v[6:7], off nt
	v_mad_u64_u32 v[4:5], s[2:3], v2, s87, v[0:1]
	v_mad_i32_i24 v5, v3, s87, v5
	v_add_u32_e32 v2, 5, v143
	v_mov_b32_e32 v3, v201
	v_lshl_add_u64 v[2:3], s[42:43], 0, v[2:3]
	v_mad_u64_u32 v[6:7], s[2:3], v2, s87, v[0:1]
	v_mad_i32_i24 v7, v3, s87, v7
	v_add_u32_e32 v2, 6, v143
	v_mov_b32_e32 v3, v201
	v_lshl_add_u64 v[2:3], s[42:43], 0, v[2:3]
	global_load_dwordx4 v[56:59], v[4:5], off nt
	global_load_dwordx4 v[52:55], v[6:7], off nt
	v_mad_u64_u32 v[4:5], s[2:3], v2, s87, v[0:1]
	v_mad_i32_i24 v5, v3, s87, v5
	v_add_u32_e32 v2, 7, v143
	v_mov_b32_e32 v3, v201
	v_lshl_add_u64 v[2:3], s[42:43], 0, v[2:3]
	v_mad_u64_u32 v[6:7], s[2:3], v2, s87, v[0:1]
	v_mad_i32_i24 v7, v3, s87, v7
	v_add_u32_e32 v2, 8, v143
	v_mov_b32_e32 v3, v201
	v_lshl_add_u64 v[2:3], s[42:43], 0, v[2:3]
	global_load_dwordx4 v[44:47], v[4:5], off nt
	global_load_dwordx4 v[8:11], v[6:7], off nt
	v_mad_u64_u32 v[4:5], s[2:3], v2, s87, v[0:1]
	v_add_u32_e32 v2, 9, v143
	v_min_u32_e32 v2, 0x1fff, v2
	v_or_b32_e32 v2, s42, v2
	v_mad_u64_u32 v[0:1], s[2:3], v2, s87, v[0:1]
	s_add_u32 s2, s50, s18
	s_addc_u32 s3, s51, 0
	s_lshl_b64 s[2:3], s[2:3], 14
	s_add_u32 s2, s58, s2
	v_mad_i32_i24 v5, v3, s87, v5
	v_mad_i32_i24 v1, s43, v203, v1
	s_addc_u32 s3, s59, s3
	global_load_dwordx4 v[4:7], v[4:5], off nt
	s_nop 0
	global_load_dwordx4 v[20:23], v[0:1], off nt
	v_lshl_add_u64 v[0:1], s[2:3], 0, v[200:201]
	v_mov_b32_e32 v129, v201
	v_lshl_add_u64 v[26:27], v[0:1], 0, v[128:129]
	v_add_co_u32_e32 v30, vcc, s88, v26
	s_add_u32 s0, s85, s0
	s_nop 0
	v_addc_co_u32_e32 v31, vcc, 0, v27, vcc
	v_add_co_u32_e32 v32, vcc, s89, v26
	s_nop 1
	v_addc_co_u32_e32 v33, vcc, 0, v27, vcc
	s_addc_u32 s1, s84, s1
	global_load_dwordx4 v[0:3], v[26:27], off nt
	global_load_dwordx4 v[108:111], v[26:27], off offset:1024 nt
	global_load_dwordx4 v[96:99], v[26:27], off offset:2048 nt
	global_load_dwordx4 v[84:87], v[26:27], off offset:3072 nt
	global_load_dwordx4 v[88:91], v[30:31], off nt
	global_load_dwordx4 v[76:79], v[30:31], off offset:1024 nt
	global_load_dwordx4 v[68:71], v[30:31], off offset:2048 nt
	global_load_dwordx4 v[64:67], v[30:31], off offset:3072 nt
	global_load_dwordx4 v[16:19], v[32:33], off nt
	global_load_dwordx4 v[116:119], v[32:33], off offset:1024 nt
	global_load_dwordx4 v[112:115], v[32:33], off offset:2048 nt
	global_load_dwordx4 v[104:107], v[32:33], off offset:3072 nt
	v_add_co_u32_e32 v26, vcc, s90, v26
	s_nop 1
	v_addc_co_u32_e32 v27, vcc, 0, v27, vcc
	global_load_dwordx4 v[100:103], v[26:27], off nt
	global_load_dwordx4 v[92:95], v[26:27], off offset:1024 nt
	global_load_dwordx4 v[80:83], v[26:27], off offset:2048 nt
	global_load_dwordx4 v[72:75], v[26:27], off offset:3072 nt
	v_mbcnt_lo_u32_b32 v29, -1, 0
	v_mbcnt_hi_u32_b32 v29, -1, v29
	v_cmp_gt_i32_e64 s[0:1], 32, v29
	s_waitcnt vmcnt(34)
	v_mul_f32_e32 v26, 0x3fb8aa3b, v24
	v_fma_f32 v27, v24, s91, -v26
	v_rndne_f32_e32 v30, v26
	v_fmac_f32_e32 v27, 0x32a5705f, v24
	v_sub_f32_e32 v26, v26, v30
	v_add_f32_e32 v26, v26, v27
	v_exp_f32_e32 v26, v26
	v_cvt_i32_f32_e32 v27, v30
	v_cmp_ngt_f32_e32 vcc, s92, v24
	v_ldexp_f32 v26, v26, v27
	s_nop 0
	v_cndmask_b32_e32 v26, 0, v26, vcc
	v_cmp_nlt_f32_e32 vcc, s93, v24
	s_nop 1
	v_cndmask_b32_e32 v24, v212, v26, vcc
	v_mul_f32_e32 v24, 0xbfb8aa3b, v24
	s_and_b64 vcc, exec, s[28:29]
	s_cbranch_vccz .LBB0_716
; __device__ __forceinline__ float shfl_from(float x, int src_lane) { return __builtin_bit_cast(float, __builtin_amdgcn_ds_bpermute(src_lane << 2, __builtin_bit_cast(int, x))); }
; __device__ __forceinline__ float incl_suffix(float x, int lane) {
; #pragma unroll
;     for (int o = 1; o < 64; o <<= 1) { const float t = shfl_from(x, lane + o < 64 ? lane + o : lane); if (lane + o < 64) x += t; }
;     return x;
; }
; __device__ __forceinline__ void vec_compute(Frame& F, const Ptrs& P, int b, int c, int h0, float v0, float v1, float* DEC) {
;     ...
;     if (dir == 0) { const float p0 = incl_prefix(v0, lane), t0 = shfl_from(p0, 63), p1 = incl_prefix(v1, lane) + t0; a0 = A2 * p0; a1 = A2 * p1; aend = shfl_from(a1, 63); }
;     else { const float s1 = incl_suffix(v1, lane), t1 = shfl_from(s1, 0), s0 = incl_suffix(v0, lane) + t1; a0 = A2 * s0; a1 = A2 * s1; aend = shfl_from(a0, 0); }
	v_cmp_gt_i32_e32 vcc, 63, v29
	v_lshlrev_b32_e32 v30, 2, v29
	v_add_u32_e32 v31, 8, v30
	v_addc_co_u32_e64 v26, s[2:3], 0, v29, vcc
	v_lshlrev_b32_e32 v26, 2, v26
	ds_bpermute_b32 v27, v26, v28
	ds_bpermute_b32 v26, v26, v25
	v_cmp_gt_i32_e64 s[2:3], 62, v29
	v_add_u32_e32 v33, 16, v30
	v_cmp_gt_i32_e64 s[4:5], 60, v29
	s_waitcnt lgkmcnt(1)
	v_add_f32_e32 v27, v28, v27
	v_cndmask_b32_e32 v27, v28, v27, vcc
	v_cndmask_b32_e64 v31, v30, v31, s[2:3]
	s_waitcnt lgkmcnt(0)
	v_add_f32_e32 v26, v25, v26
	ds_bpermute_b32 v32, v31, v27
	v_cndmask_b32_e32 v26, v25, v26, vcc
	ds_bpermute_b32 v31, v31, v26
	v_add_u32_e32 v34, 32, v30
	v_cmp_gt_i32_e64 s[6:7], 56, v29
	s_waitcnt lgkmcnt(1)
	v_add_f32_e32 v32, v27, v32
	v_cndmask_b32_e64 v27, v27, v32, s[2:3]
	v_cndmask_b32_e64 v32, v30, v33, s[4:5]
	s_waitcnt lgkmcnt(0)
	v_add_f32_e32 v31, v26, v31
	ds_bpermute_b32 v33, v32, v27
	v_cndmask_b32_e64 v26, v26, v31, s[2:3]
	ds_bpermute_b32 v31, v32, v26
	v_add_u32_e32 v32, 64, v30
	v_cmp_gt_i32_e32 vcc, 48, v29
	s_waitcnt lgkmcnt(1)
	v_add_f32_e32 v33, v27, v33
	v_cndmask_b32_e64 v27, v27, v33, s[4:5]
	v_cndmask_b32_e64 v33, v30, v34, s[6:7]
	s_waitcnt lgkmcnt(0)
	v_add_f32_e32 v31, v26, v31
	ds_bpermute_b32 v34, v33, v27
	v_cndmask_b32_e64 v26, v26, v31, s[4:5]
	ds_bpermute_b32 v31, v33, v26
	v_cndmask_b32_e32 v32, v30, v32, vcc
	s_waitcnt lgkmcnt(1)
	v_add_f32_e32 v34, v27, v34
	v_cndmask_b32_e64 v27, v27, v34, s[6:7]
	s_waitcnt lgkmcnt(0)
	v_add_f32_e32 v31, v26, v31
	ds_bpermute_b32 v34, v32, v27
	v_cndmask_b32_e64 v26, v26, v31, s[6:7]
	ds_bpermute_b32 v31, v32, v26
	v_add_u32_e32 v32, 0x80, v30
	v_cndmask_b32_e64 v30, v30, v32, s[0:1]
	s_waitcnt lgkmcnt(1)
	v_add_f32_e32 v33, v27, v34
	v_cndmask_b32_e32 v27, v27, v33, vcc
	s_waitcnt lgkmcnt(0)
	v_add_f32_e32 v31, v26, v31
	ds_bpermute_b32 v32, v30, v27
	v_cndmask_b32_e32 v31, v26, v31, vcc
	ds_bpermute_b32 v30, v30, v31
	s_waitcnt lgkmcnt(1)
	v_add_f32_e32 v26, v27, v32
	v_cndmask_b32_e64 v26, v27, v26, s[0:1]
	s_waitcnt lgkmcnt(0)
	v_add_f32_e32 v27, v31, v30
	v_readlane_b32 s2, v26, 0
	v_cndmask_b32_e64 v27, v31, v27, s[0:1]
	s_nop 0
	v_add_f32_e32 v27, s2, v27
	v_pk_mul_f32 v[26:27], v[24:25], v[26:27] op_sel_hi:[0,1]
	s_nop 0
	v_readlane_b32 s2, v27, 0
	s_cbranch_execz .LBB0_717
	s_branch .LBB0_718

;     __device__ __forceinline__ int lane_() const { return hw_lane(); }
; __device__ __forceinline__ float shfl_from(float x, int src_lane) { return __builtin_bit_cast(float, __builtin_amdgcn_ds_bpermute(src_lane << 2, __builtin_bit_cast(int, x))); }
; __device__ __forceinline__ void vec_load(Frame& F, const Ptrs& P, int b, int c, int h0, float& v0, float& v1) {
;     const float* DT = (const float*)(P.ws + WS_DT);
;     const int lane = F.lane_(), hl = F.wave >> 1, dir = F.wave & 1, h = h0 + hl;
;     const size_t row0 = (size_t)b * SEQ + c * 128;
;     v0 = DT[(row0 + lane) * 32 + dir * 16 + h]; v1 = DT[(row0 + 64 + lane) * 32 + dir * 16 + h];
; }
; __device__ __forceinline__ void vec_compute(Frame& F, const Ptrs& P, int b, int c, int h0, float v0, float v1, float* DEC) {
;     const int lane = F.lane_(), hl = F.wave >> 1, dir = F.wave & 1, h = h0 + hl;
;     const float A2 = -expf(dir ? P.alb[h] : P.alf[h]) * LOG2E;
;     float a0, a1, aend;
;     if (dir == 0) { const float p0 = incl_prefix(v0, lane), t0 = shfl_from(p0, 63), p1 = incl_prefix(v1, lane) + t0; a0 = A2 * p0; a1 = A2 * p1; aend = shfl_from(a1, 63); }
;     else { const float s1 = incl_suffix(v1, lane), t1 = shfl_from(s1, 0), s0 = incl_suffix(v0, lane) + t1; a0 = A2 * s0; a1 = A2 * s1; aend = shfl_from(a0, 0); }
; template <class Wait>
; __device__ __forceinline__ void out_unit(Frame& F, const Ptrs& P, int b, int c, int g, const Wait& wait) {
;     ...
;     if (hh == 0) {
;     float dv0, dv1; vec_load(F, P, b, c, h0, dv0, dv1);
;     ConvRaw R1; const int mat1 = tid >> 8, ch1 = tid & 15, rg1 = (tid >> 4) & 15, col1 = (mat1 ? 1024 : 1280) + g * 128 + 8 * ch1;
;     conv_load(R1, XBC, b, c, col1, rg1);
;     vec_compute(F, P, b, c, h0, dv0, dv1, nullptr);
.LBB0_719:
	s_and_b64 vcc, exec, s[0:1]
	s_cbranch_vccz .LBB0_742
	v_mbcnt_lo_u32_b32 v0, -1, 0
	v_mbcnt_hi_u32_b32 v0, -1, v0
	s_lshl_b64 s[2:3], s[18:19], 2
	v_ashrrev_i32_e32 v1, 31, v0
	v_lshl_add_u64 v[2:3], s[44:45], 0, v[0:1]
	v_lshl_add_u64 v[0:1], s[46:47], 0, v[0:1]
	v_lshlrev_b64 v[2:3], 7, v[2:3]
	v_lshlrev_b64 v[0:1], 7, v[0:1]
	v_lshl_add_u64 v[2:3], s[22:23], 0, v[2:3]
	v_lshl_add_u64 v[0:1], s[22:23], 0, v[0:1]
	s_movk_i32 s0, 0x100
	v_lshl_add_u64 v[2:3], v[2:3], 0, s[2:3]
	v_lshl_add_u64 v[0:1], v[0:1], 0, s[2:3]
	v_and_b32_e32 v132, 15, v224
	v_cmp_gt_u32_e64 s[0:1], s0, v224
	global_load_dword v20, v[2:3], off nt
	global_load_dword v21, v[0:1], off nt
	v_bfe_u32 v80, v224, 4, 4
	v_cndmask_b32_e64 v0, v219, v220, s[0:1]
	v_lshlrev_b32_e32 v1, 3, v132
	v_or3_b32 v17, v0, s65, v1
	v_lshlrev_b32_e32 v74, 3, v80
	v_add_u32_e32 v14, s64, v74
	v_lshlrev_b32_e32 v0, 1, v17
	v_mov_b32_e32 v1, v201
	v_lshl_add_u64 v[12:13], s[14:15], 0, v[0:1]
	v_max_i32_e32 v0, 0, v14
	v_lshl_add_u64 v[0:1], s[42:43], 0, v[0:1]
	v_mad_u64_u32 v[2:3], s[4:5], v0, s87, v[12:13]
	v_or_b32_e32 v0, s13, v74
	v_or_b32_e32 v0, s42, v0
	v_mad_i32_i24 v3, v1, s87, v3
	v_mad_u64_u32 v[0:1], s[4:5], v0, s87, v[12:13]
	v_mad_i32_i24 v1, s43, v203, v1
	global_load_dwordx4 v[8:11], v[2:3], off nt
	global_load_dwordx4 v[56:59], v[0:1], off nt
	v_add_u32_e32 v0, 2, v14
	v_mov_b32_e32 v1, v201
	v_lshl_add_u64 v[0:1], s[42:43], 0, v[0:1]
	v_mad_u64_u32 v[2:3], s[4:5], v0, s87, v[12:13]
	v_mad_i32_i24 v3, v1, s87, v3
	v_add_u32_e32 v0, 3, v14
	v_mov_b32_e32 v1, v201
	v_lshl_add_u64 v[0:1], s[42:43], 0, v[0:1]
	global_load_dwordx4 v[60:63], v[2:3], off nt
	v_mad_u64_u32 v[2:3], s[4:5], v0, s87, v[12:13]
	v_mad_i32_i24 v3, v1, s87, v3
	v_add_u32_e32 v0, 4, v14
	v_mov_b32_e32 v1, v201
	v_lshl_add_u64 v[0:1], s[42:43], 0, v[0:1]
	global_load_dwordx4 v[52:55], v[2:3], off nt
	v_mad_u64_u32 v[2:3], s[4:5], v0, s87, v[12:13]
	v_mad_i32_i24 v3, v1, s87, v3
	v_add_u32_e32 v0, 5, v14
	v_mov_b32_e32 v1, v201
	v_lshl_add_u64 v[0:1], s[42:43], 0, v[0:1]
	global_load_dwordx4 v[48:51], v[2:3], off nt
	v_mad_u64_u32 v[2:3], s[4:5], v0, s87, v[12:13]
	v_mad_i32_i24 v3, v1, s87, v3
	v_add_u32_e32 v0, 6, v14
	v_mov_b32_e32 v1, v201
	v_lshl_add_u64 v[0:1], s[42:43], 0, v[0:1]
	global_load_dwordx4 v[44:47], v[2:3], off nt
	v_mad_u64_u32 v[2:3], s[4:5], v0, s87, v[12:13]
	v_mad_i32_i24 v3, v1, s87, v3
	v_add_u32_e32 v0, 7, v14
	v_mov_b32_e32 v1, v201
	v_lshl_add_u64 v[0:1], s[42:43], 0, v[0:1]
	global_load_dwordx4 v[40:43], v[2:3], off nt
	v_mad_u64_u32 v[2:3], s[4:5], v0, s87, v[12:13]
	v_add_u32_e32 v0, 8, v14
	v_add_u32_e32 v14, 9, v14
	v_mad_i32_i24 v3, v1, s87, v3
	v_mov_b32_e32 v1, v201
	v_min_u32_e32 v14, 0x1fff, v14
	v_lshl_add_u64 v[0:1], s[42:43], 0, v[0:1]
	v_or_b32_e32 v14, s42, v14
	global_load_dwordx4 v[4:7], v[2:3], off nt
	v_mad_u64_u32 v[2:3], s[4:5], v0, s87, v[12:13]
	v_mad_u64_u32 v[12:13], s[4:5], v14, s87, v[12:13]
	s_add_u32 s2, s85, s2
	v_mad_i32_i24 v3, v1, s87, v3
	v_mad_i32_i24 v13, s43, v203, v13
	s_addc_u32 s3, s84, s3
	global_load_dwordx4 v[0:3], v[2:3], off nt
	s_nop 0
	global_load_dwordx4 v[12:15], v[12:13], off nt
	v_mbcnt_lo_u32_b32 v22, -1, 0
	v_mbcnt_hi_u32_b32 v22, -1, v22
	global_load_dword v16, v201, s[2:3] nt
	v_cmp_gt_i32_e64 s[2:3], 32, v22
	s_waitcnt vmcnt(0)
	v_mul_f32_e32 v18, 0x3fb8aa3b, v16
	v_fma_f32 v19, v16, s91, -v18
	v_rndne_f32_e32 v23, v18
	v_fmac_f32_e32 v19, 0x32a5705f, v16
	v_sub_f32_e32 v18, v18, v23
	v_add_f32_e32 v18, v18, v19
	v_exp_f32_e32 v18, v18
	v_cvt_i32_f32_e32 v19, v23
	v_cmp_ngt_f32_e32 vcc, s92, v16
	v_ldexp_f32 v18, v18, v19
	s_nop 0
	v_cndmask_b32_e32 v18, 0, v18, vcc
	v_cmp_nlt_f32_e32 vcc, s93, v16
	s_nop 1
	v_cndmask_b32_e32 v16, v212, v18, vcc
	v_mul_f32_e32 v16, 0xbfb8aa3b, v16
	s_and_b64 vcc, exec, s[28:29]
	s_cbranch_vccz .LBB0_722
	v_cmp_gt_i32_e32 vcc, 63, v22
	v_lshlrev_b32_e32 v23, 2, v22
	v_add_u32_e32 v24, 8, v23
	v_addc_co_u32_e64 v18, s[4:5], 0, v22, vcc
	v_lshlrev_b32_e32 v18, 2, v18
	ds_bpermute_b32 v19, v18, v21
	ds_bpermute_b32 v18, v18, v20
	v_cmp_gt_i32_e64 s[4:5], 62, v22
	v_add_u32_e32 v26, 16, v23
	v_cmp_gt_i32_e64 s[6:7], 60, v22
	s_waitcnt lgkmcnt(1)
	v_add_f32_e32 v19, v21, v19
	v_cndmask_b32_e32 v19, v21, v19, vcc
	v_cndmask_b32_e64 v24, v23, v24, s[4:5]
	s_waitcnt lgkmcnt(0)
	v_add_f32_e32 v18, v20, v18
	ds_bpermute_b32 v25, v24, v19
	v_cndmask_b32_e32 v18, v20, v18, vcc
	ds_bpermute_b32 v24, v24, v18
	v_add_u32_e32 v27, 32, v23
	v_cmp_gt_i32_e64 s[8:9], 56, v22
	s_waitcnt lgkmcnt(1)
	v_add_f32_e32 v25, v19, v25
	v_cndmask_b32_e64 v19, v19, v25, s[4:5]
	v_cndmask_b32_e64 v25, v23, v26, s[6:7]
	s_waitcnt lgkmcnt(0)
	v_add_f32_e32 v24, v18, v24
	ds_bpermute_b32 v26, v25, v19
	v_cndmask_b32_e64 v18, v18, v24, s[4:5]
	ds_bpermute_b32 v24, v25, v18
	v_add_u32_e32 v25, 64, v23
	v_cmp_gt_i32_e32 vcc, 48, v22
	s_waitcnt lgkmcnt(1)
	v_add_f32_e32 v26, v19, v26
	v_cndmask_b32_e64 v19, v19, v26, s[6:7]
	v_cndmask_b32_e64 v26, v23, v27, s[8:9]
	s_waitcnt lgkmcnt(0)
	v_add_f32_e32 v24, v18, v24
	ds_bpermute_b32 v27, v26, v19
	v_cndmask_b32_e64 v18, v18, v24, s[6:7]
	ds_bpermute_b32 v24, v26, v18
	v_cndmask_b32_e32 v25, v23, v25, vcc
	s_waitcnt lgkmcnt(1)
	v_add_f32_e32 v27, v19, v27
	v_cndmask_b32_e64 v19, v19, v27, s[8:9]
	s_waitcnt lgkmcnt(0)
	v_add_f32_e32 v24, v18, v24
	ds_bpermute_b32 v27, v25, v19
	v_cndmask_b32_e64 v18, v18, v24, s[8:9]
	ds_bpermute_b32 v24, v25, v18
	v_add_u32_e32 v25, 0x80, v23
	v_cndmask_b32_e64 v23, v23, v25, s[2:3]
	s_waitcnt lgkmcnt(1)
	v_add_f32_e32 v26, v19, v27
	v_cndmask_b32_e32 v19, v19, v26, vcc
	s_waitcnt lgkmcnt(0)
	v_add_f32_e32 v24, v18, v24
	ds_bpermute_b32 v25, v23, v19
	v_cndmask_b32_e32 v24, v18, v24, vcc
	ds_bpermute_b32 v23, v23, v24
	s_waitcnt lgkmcnt(1)
	v_add_f32_e32 v18, v19, v25
	v_cndmask_b32_e64 v18, v19, v18, s[2:3]
	s_waitcnt lgkmcnt(0)
	v_add_f32_e32 v19, v24, v23
	v_readlane_b32 s4, v18, 0
	v_cndmask_b32_e64 v19, v24, v19, s[2:3]
	s_nop 0
	v_add_f32_e32 v19, s4, v19
	v_pk_mul_f32 v[18:19], v[16:17], v[18:19] op_sel_hi:[0,1]
	s_nop 0
	v_readlane_b32 s4, v19, 0
	s_cbranch_execz .LBB0_723
	s_branch .LBB0_724

; #define LAS __attribute__((address_space(3)))
; template <class Put>
; __device__ __forceinline__ void conv_compute(const ConvRaw& R, const float* cw, const float* cb, int col0, int rg, const Put& put) {
;     const f32x4 w0a = *(const f32x4*)(cw + col0), w0b = *(const f32x4*)(cw + col0 + 4), w1a = *(const f32x4*)(cw + XBCW + col0), w1b = *(const f32x4*)(cw + XBCW + col0 + 4);
;     const f32x4 w2a = *(const f32x4*)(cw + 2 * XBCW + col0), w2b = *(const f32x4*)(cw + 2 * XBCW + col0 + 4), ba = *(const f32x4*)(cb + col0), bb = *(const f32x4*)(cb + col0 + 4);
;     const int r0 = 8 * rg;
; #pragma unroll
;     for (int rr = 0; rr < 8; ++rr) {
;         const u32x4 xm = R.r[rr], x0 = R.r[rr + 1], xp = R.r[rr + 2]; u32x4 o;
; #pragma unroll
;         for (int e = 0; e < 4; ++e) {
;             const float wl0 = e < 2 ? w0a[2 * e] : w0b[2 * e - 4], wh0 = e < 2 ? w0a[2 * e + 1] : w0b[2 * e - 3];
;             const float wl1 = e < 2 ? w1a[2 * e] : w1b[2 * e - 4], wh1 = e < 2 ? w1a[2 * e + 1] : w1b[2 * e - 3];
;             const float wl2 = e < 2 ? w2a[2 * e] : w2b[2 * e - 4], wh2 = e < 2 ? w2a[2 * e + 1] : w2b[2 * e - 3];
;             const float bl = e < 2 ? ba[2 * e] : bb[2 * e - 4], bh = e < 2 ? ba[2 * e + 1] : bb[2 * e - 3];
; __device__ __forceinline__ void vec_compute(Frame& F, const Ptrs& P, int b, int c, int h0, float v0, float v1, float* DEC) {
;     const int lane = F.lane_(), hl = F.wave >> 1, dir = F.wave & 1, h = h0 + hl;
;     const float A2 = -expf(dir ? P.alb[h] : P.alf[h]) * LOG2E;
;     float a0, a1, aend;
;     if (dir == 0) { const float p0 = incl_prefix(v0, lane), t0 = shfl_from(p0, 63), p1 = incl_prefix(v1, lane) + t0; a0 = A2 * p0; a1 = A2 * p1; aend = shfl_from(a1, 63); }
;     else { const float s1 = incl_suffix(v1, lane), t1 = shfl_from(s1, 0), s0 = incl_suffix(v0, lane) + t1; a0 = A2 * s0; a1 = A2 * s1; aend = shfl_from(a0, 0); }
;     LAS float* V = (LAS float*)(F.lds + L_VEC) + (hl * 2 + dir) * 512;
;     const float g0 = a0 - log2f(v0), g1 = a1 - log2f(v1);
;     V[lane] = a0; V[64 + lane] = a1; V[128 + lane] = g0; V[192 + lane] = g1; V[256 + lane] = v0; V[320 + lane] = v1;
;     V[384 + lane] = __builtin_amdgcn_exp2f(aend - g0); V[448 + lane] = __builtin_amdgcn_exp2f(aend - g1);
;     if (DEC && lane == 0) DEC[(((size_t)b * 64 + c) * 2 + dir) * 16 + h] = __builtin_amdgcn_exp2f(aend);
; }
.LBB0_724:
	v_or_b32_e32 v16, s97, v80
	v_cmp_ne_u32_e32 vcc, 0, v16
	v_lshlrev_b32_e32 v36, 2, v17
	v_lshlrev_b32_e32 v68, 16, v56
	v_cndmask_b32_e32 v81, 0, v11, vcc
	v_cndmask_b32_e32 v82, 0, v10, vcc
	v_cndmask_b32_e32 v72, 0, v9, vcc
	v_cndmask_b32_e32 v65, 0, v8, vcc
	v_cmp_eq_u32_e32 vcc, 15, v80
	s_and_b64 s[2:3], s[48:49], vcc
	v_cmp_gt_f32_e32 vcc, s94, v20
	v_cndmask_b32_e64 v76, v15, 0, s[2:3]
	v_cndmask_b32_e64 v77, v14, 0, s[2:3]
	v_cndmask_b32_e32 v8, 0, v218, vcc
	v_cndmask_b32_e64 v9, 0, 32, vcc
	v_cmp_gt_f32_e32 vcc, s94, v21
	v_ldexp_f32 v9, v20, v9
	v_log_f32_e32 v9, v9
	v_cndmask_b32_e64 v10, 0, 32, vcc
	v_ldexp_f32 v10, v21, v10
	v_log_f32_e32 v10, v10
	v_sub_f32_e32 v8, v9, v8
	v_cndmask_b32_e32 v9, 0, v218, vcc
	v_sub_f32_e32 v8, v19, v8
	v_sub_f32_e32 v9, v10, v9
	v_sub_f32_e32 v9, v18, v9
	v_lshl_add_u32 v10, v22, 2, s86
	ds_write2st64_b32 v10, v19, v18 offset1:1
	ds_write2st64_b32 v10, v8, v9 offset0:2 offset1:3
	ds_write2st64_b32 v10, v20, v21 offset0:4 offset1:5
	v_sub_f32_e32 v8, s4, v8
	v_sub_f32_e32 v9, s4, v9
	v_exp_f32_e32 v8, v8
	v_exp_f32_e32 v9, v9
	v_cndmask_b32_e64 v78, v13, 0, s[2:3]
	v_cndmask_b32_e64 v79, v12, 0, s[2:3]
	v_lshlrev_b32_e32 v64, 16, v65
	ds_write2st64_b32 v10, v8, v9 offset0:6 offset1:7
	v_cndmask_b32_e64 v8, v221, 0, s[0:1]
	v_add_u32_e32 v75, 0, v8
	global_load_dwordx4 v[8:11], v36, s[24:25] offset:16 nt
	global_load_dwordx4 v[24:27], v36, s[24:25] nt
	global_load_dwordx4 v[16:19], v36, s[30:31] offset:16 nt
	global_load_dwordx4 v[28:31], v36, s[30:31] nt
	global_load_dwordx4 v[12:15], v36, s[36:37] offset:16 nt
	global_load_dwordx4 v[32:35], v36, s[36:37] nt
	global_load_dwordx4 v[20:23], v36, s[26:27] offset:16 nt
	s_nop 0
	global_load_dwordx4 v[36:39], v36, s[26:27] nt
	v_and_b32_e32 v65, 0xffff0000, v65
	v_and_b32_e32 v69, 0xffff0000, v56
	v_lshlrev_b32_e32 v80, 11, v80
	v_or_b32_e32 v202, s68, v222
	v_or_b32_e32 v120, 32, v202
	v_lshlrev_b32_e32 v121, 8, v202
	v_lshlrev_b32_e32 v122, 8, v120
	v_cmp_eq_u32_e32 vcc, 15, v141
	v_lshlrev_b32_e32 v204, 3, v223
	s_waitcnt vmcnt(0)
	v_pk_fma_f32 v[64:65], v[24:25], v[64:65], v[36:37]
	s_nop 0
	v_pk_fma_f32 v[66:67], v[28:29], v[68:69], v[64:65]
	v_lshlrev_b32_e32 v64, 16, v60
	v_and_b32_e32 v65, 0xffff0000, v60
	v_pk_fma_f32 v[66:67], v[32:33], v[64:65], v[66:67]
	v_lshlrev_b32_e32 v60, 16, v61
	v_mul_f32_e32 v56, 0xbfb8aa3b, v66
	v_exp_f32_e32 v56, v56
	v_and_b32_e32 v61, 0xffff0000, v61
	v_add_f32_e32 v56, 1.0, v56
	v_rcp_f32_e32 v70, v56
	v_mul_f32_e32 v56, 0xbfb8aa3b, v67
	v_exp_f32_e32 v56, v56
	s_nop 0
	v_add_f32_e32 v56, 1.0, v56
	v_rcp_f32_e32 v71, v56
	s_nop 0
	v_pk_mul_f32 v[66:67], v[66:67], v[70:71]
	s_nop 0
	v_cvt_pk_bf16_f32 v56, v66, v67
	v_lshlrev_b32_e32 v66, 16, v72
	v_and_b32_e32 v67, 0xffff0000, v72
	v_pk_fma_f32 v[66:67], v[26:27], v[66:67], v[38:39]
	v_lshlrev_b32_e32 v70, 16, v57
	v_and_b32_e32 v71, 0xffff0000, v57
	v_pk_fma_f32 v[66:67], v[30:31], v[70:71], v[66:67]
	s_nop 0
	v_pk_fma_f32 v[66:67], v[34:35], v[60:61], v[66:67]
	s_nop 0
	v_mul_f32_e32 v57, 0xbfb8aa3b, v66
	v_exp_f32_e32 v57, v57
	s_nop 0
	v_add_f32_e32 v57, 1.0, v57
	v_rcp_f32_e32 v72, v57
	v_mul_f32_e32 v57, 0xbfb8aa3b, v67
	v_exp_f32_e32 v57, v57
	s_nop 0
	v_add_f32_e32 v57, 1.0, v57
	v_rcp_f32_e32 v73, v57
	s_nop 0
	v_pk_mul_f32 v[66:67], v[66:67], v[72:73]
	s_nop 0
	v_cvt_pk_bf16_f32 v57, v66, v67
	v_lshlrev_b32_e32 v66, 16, v82
	v_and_b32_e32 v67, 0xffff0000, v82
	v_pk_fma_f32 v[66:67], v[8:9], v[66:67], v[20:21]
	v_lshlrev_b32_e32 v72, 16, v58
	v_and_b32_e32 v73, 0xffff0000, v58
	v_pk_fma_f32 v[82:83], v[16:17], v[72:73], v[66:67]
	v_lshlrev_b32_e32 v66, 16, v62
	v_and_b32_e32 v67, 0xffff0000, v62
	v_pk_fma_f32 v[82:83], v[12:13], v[66:67], v[82:83]
	v_lshlrev_b32_e32 v62, 16, v63
	v_mul_f32_e32 v58, 0xbfb8aa3b, v82
	v_exp_f32_e32 v58, v58
	v_and_b32_e32 v63, 0xffff0000, v63
	v_add_f32_e32 v58, 1.0, v58
	v_rcp_f32_e32 v84, v58
	v_mul_f32_e32 v58, 0xbfb8aa3b, v83
	v_exp_f32_e32 v58, v58
	s_nop 0
	v_add_f32_e32 v58, 1.0, v58
	v_rcp_f32_e32 v85, v58
	s_nop 0
	v_pk_mul_f32 v[82:83], v[82:83], v[84:85]
	s_nop 0
	v_cvt_pk_bf16_f32 v58, v82, v83
	v_lshlrev_b32_e32 v82, 16, v81
	v_and_b32_e32 v83, 0xffff0000, v81
	v_pk_fma_f32 v[82:83], v[10:11], v[82:83], v[22:23]
	v_lshlrev_b32_e32 v84, 16, v59
	v_and_b32_e32 v85, 0xffff0000, v59
	v_pk_fma_f32 v[82:83], v[18:19], v[84:85], v[82:83]
	v_bitop3_b32 v81, v74, v132, 8 bitop3:0x6c
	v_pk_fma_f32 v[82:83], v[14:15], v[62:63], v[82:83]
	v_lshlrev_b32_e32 v81, 4, v81
	v_mul_f32_e32 v59, 0xbfb8aa3b, v82
	v_exp_f32_e32 v59, v59
	v_add3_u32 v80, v75, v80, v81
	v_add_f32_e32 v59, 1.0, v59
	v_rcp_f32_e32 v86, v59
	v_mul_f32_e32 v59, 0xbfb8aa3b, v83
	v_exp_f32_e32 v59, v59
	s_nop 0
	v_add_f32_e32 v59, 1.0, v59
	v_rcp_f32_e32 v87, v59
	s_nop 0
	v_pk_mul_f32 v[82:83], v[82:83], v[86:87]
	s_nop 0
	v_cvt_pk_bf16_f32 v59, v82, v83
	ds_write_b128 v80, v[56:59]
	v_pk_fma_f32 v[56:57], v[24:25], v[68:69], v[36:37]
	v_lshlrev_b32_e32 v58, 16, v52
	v_pk_fma_f32 v[56:57], v[28:29], v[64:65], v[56:57]
	v_and_b32_e32 v59, 0xffff0000, v52
	v_pk_fma_f32 v[56:57], v[32:33], v[58:59], v[56:57]
	v_add_u32_e32 v86, 0, v121
	v_mul_f32_e32 v52, 0xbfb8aa3b, v56
	v_exp_f32_e32 v52, v52
	v_add_u32_e32 v87, 0, v122
	v_add_f32_e32 v52, 1.0, v52
	v_rcp_f32_e32 v68, v52
	v_mul_f32_e32 v52, 0xbfb8aa3b, v57
	v_exp_f32_e32 v52, v52
	s_nop 0
	v_add_f32_e32 v52, 1.0, v52
	v_rcp_f32_e32 v69, v52
	s_nop 0
	v_pk_mul_f32 v[56:57], v[56:57], v[68:69]
	s_nop 0
	v_cvt_pk_bf16_f32 v80, v56, v57
	v_pk_fma_f32 v[56:57], v[26:27], v[70:71], v[38:39]
	v_lshlrev_b32_e32 v70, 16, v54
	v_pk_fma_f32 v[68:69], v[30:31], v[60:61], v[56:57]
; __device__ __forceinline__ unsigned cvtpk(float lo, float hi) { f32x2_t v = {lo, hi}; bf16x2_t b = __builtin_convertvector(v, bf16x2_t); return __builtin_bit_cast(unsigned, b); }
; __device__ __forceinline__ float lo16(unsigned u) { return __uint_as_float(u << 16); }
; __device__ __forceinline__ float hi16(unsigned u) { return __uint_as_float(u & 0xffff0000u); }
; __device__ __forceinline__ float silu_fast(float v) { return v * __builtin_amdgcn_rcpf(1.f + __builtin_amdgcn_exp2f(-v * LOG2E)); }
; __device__ __forceinline__ float lo16(unsigned u) { return __uint_as_float(u << 16); }
; template <class Put>
; __device__ __forceinline__ void conv_compute(const ConvRaw& R, const float* cw, const float* cb, int col0, int rg, const Put& put) {
;     const f32x4 w0a = *(const f32x4*)(cw + col0), w0b = *(const f32x4*)(cw + col0 + 4), w1a = *(const f32x4*)(cw + XBCW + col0), w1b = *(const f32x4*)(cw + XBCW + col0 + 4);
;     const f32x4 w2a = *(const f32x4*)(cw + 2 * XBCW + col0), w2b = *(const f32x4*)(cw + 2 * XBCW + col0 + 4), ba = *(const f32x4*)(cb + col0), bb = *(const f32x4*)(cb + col0 + 4);
;     const int r0 = 8 * rg;
; #pragma unroll
;     for (int rr = 0; rr < 8; ++rr) {
;         const u32x4 xm = R.r[rr], x0 = R.r[rr + 1], xp = R.r[rr + 2]; u32x4 o;
; #pragma unroll
;         for (int e = 0; e < 4; ++e) {
;             const float wl0 = e < 2 ? w0a[2 * e] : w0b[2 * e - 4], wh0 = e < 2 ? w0a[2 * e + 1] : w0b[2 * e - 3];
;             const float wl1 = e < 2 ? w1a[2 * e] : w1b[2 * e - 4], wh1 = e < 2 ? w1a[2 * e + 1] : w1b[2 * e - 3];
;             const float wl2 = e < 2 ? w2a[2 * e] : w2b[2 * e - 4], wh2 = e < 2 ? w2a[2 * e + 1] : w2b[2 * e - 3];
;             const float bl = e < 2 ? ba[2 * e] : bb[2 * e - 4], bh = e < 2 ? ba[2 * e + 1] : bb[2 * e - 3];
;             const float vl = bl + wl0 * lo16(xm[e]) + wl1 * lo16(x0[e]) + wl2 * lo16(xp[e]);
;             const float vh = bh + wh0 * hi16(xm[e]) + wh1 * hi16(x0[e]) + wh2 * hi16(xp[e]);
;             o[e] = cvtpk(silu_fast(vl), silu_fast(vh));
;         }
;         put(r0 + rr, o);
;     }
; }
; template <class Wait>
; __device__ __forceinline__ void out_unit(Frame& F, const Ptrs& P, int b, int c, int g, const Wait& wait) {
;     ...
;     conv_compute(R1, P.conv_w, P.conv_b, col1, rg1, PutRow{lds + (mat1 ? L_BROW : L_CIMG), ch1});
	v_lshlrev_b32_e32 v56, 16, v53
	v_and_b32_e32 v57, 0xffff0000, v53
	v_pk_fma_f32 v[52:53], v[34:35], v[56:57], v[68:69]
	v_and_b32_e32 v71, 0xffff0000, v54
	v_mul_f32_e32 v68, 0xbfb8aa3b, v52
	v_mul_f32_e32 v69, 0xbfb8aa3b, v53
	v_exp_f32_e32 v68, v68
	v_exp_f32_e32 v69, v69
	v_add_f32_e32 v68, 1.0, v68
	v_add_f32_e32 v69, 1.0, v69
	v_rcp_f32_e32 v68, v68
	v_rcp_f32_e32 v69, v69
	s_nop 0
	v_pk_mul_f32 v[52:53], v[52:53], v[68:69]
	s_nop 0
	v_cvt_pk_bf16_f32 v81, v52, v53
	v_pk_fma_f32 v[52:53], v[8:9], v[72:73], v[20:21]
	v_lshl_add_u32 v73, v222, 8, s70
	v_pk_fma_f32 v[52:53], v[16:17], v[66:67], v[52:53]
	v_or_b32_e32 v72, s97, v141
	v_pk_fma_f32 v[52:53], v[12:13], v[70:71], v[52:53]
	s_nop 0
	v_mul_f32_e32 v54, 0xbfb8aa3b, v52
	v_exp_f32_e32 v54, v54
	s_nop 0
	v_add_f32_e32 v54, 1.0, v54
	v_rcp_f32_e32 v68, v54
	v_mul_f32_e32 v54, 0xbfb8aa3b, v53
	v_exp_f32_e32 v54, v54
	s_nop 0
	v_add_f32_e32 v54, 1.0, v54
	v_rcp_f32_e32 v69, v54
	s_nop 0
	v_pk_mul_f32 v[52:53], v[52:53], v[68:69]
	s_nop 0
	v_cvt_pk_bf16_f32 v82, v52, v53
	v_pk_fma_f32 v[52:53], v[10:11], v[84:85], v[22:23]
	s_nop 0
	v_pk_fma_f32 v[68:69], v[18:19], v[62:63], v[52:53]
	v_lshlrev_b32_e32 v52, 16, v55
	v_and_b32_e32 v53, 0xffff0000, v55
	v_pk_fma_f32 v[54:55], v[14:15], v[52:53], v[68:69]
	s_nop 0
	v_mul_f32_e32 v68, 0xbfb8aa3b, v54
	v_mul_f32_e32 v69, 0xbfb8aa3b, v55
	v_exp_f32_e32 v68, v68
	v_exp_f32_e32 v69, v69
	v_add_f32_e32 v68, 1.0, v68
	v_add_f32_e32 v69, 1.0, v69
	v_rcp_f32_e32 v68, v68
	v_rcp_f32_e32 v69, v69
	s_nop 0
	v_pk_mul_f32 v[54:55], v[54:55], v[68:69]
	s_nop 0
	v_cvt_pk_bf16_f32 v83, v54, v55
	v_or_b32_e32 v54, 1, v74
	v_lshlrev_b32_e32 v55, 8, v54
	v_bitop3_b32 v54, v54, v132, 9 bitop3:0x6c
	v_lshlrev_b32_e32 v54, 4, v54
	v_add3_u32 v54, v75, v55, v54
	ds_write_b128 v54, v[80:83]
	v_pk_fma_f32 v[54:55], v[24:25], v[64:65], v[36:37]
	v_lshlrev_b32_e32 v68, 16, v48
	v_pk_fma_f32 v[54:55], v[28:29], v[58:59], v[54:55]
	v_and_b32_e32 v69, 0xffff0000, v48
	v_pk_fma_f32 v[54:55], v[32:33], v[68:69], v[54:55]
	s_nop 0
	v_mul_f32_e32 v48, 0xbfb8aa3b, v54
	v_exp_f32_e32 v48, v48
	s_nop 0
	v_add_f32_e32 v48, 1.0, v48
	v_rcp_f32_e32 v64, v48
	v_mul_f32_e32 v48, 0xbfb8aa3b, v55
	v_exp_f32_e32 v48, v48
	s_nop 0
	v_add_f32_e32 v48, 1.0, v48
	v_rcp_f32_e32 v65, v48
	v_lshlrev_b32_e32 v48, 16, v49
	v_and_b32_e32 v49, 0xffff0000, v49
	v_pk_mul_f32 v[54:55], v[54:55], v[64:65]
	s_nop 0
	v_cvt_pk_bf16_f32 v80, v54, v55
	v_pk_fma_f32 v[54:55], v[26:27], v[60:61], v[38:39]
	v_lshlrev_b32_e32 v64, 16, v50
	v_pk_fma_f32 v[54:55], v[30:31], v[56:57], v[54:55]
	v_and_b32_e32 v65, 0xffff0000, v50
	v_pk_fma_f32 v[54:55], v[34:35], v[48:49], v[54:55]
	s_nop 0
	v_mul_f32_e32 v60, 0xbfb8aa3b, v54
	v_mul_f32_e32 v61, 0xbfb8aa3b, v55
	v_exp_f32_e32 v60, v60
	v_exp_f32_e32 v61, v61
	v_add_f32_e32 v60, 1.0, v60
	v_add_f32_e32 v61, 1.0, v61
	v_rcp_f32_e32 v60, v60
	v_rcp_f32_e32 v61, v61
	s_nop 0
	v_pk_mul_f32 v[54:55], v[54:55], v[60:61]
	s_nop 0
	v_cvt_pk_bf16_f32 v81, v54, v55
	v_pk_fma_f32 v[54:55], v[8:9], v[66:67], v[20:21]
	s_nop 0
	v_pk_fma_f32 v[54:55], v[16:17], v[70:71], v[54:55]
	s_nop 0
	v_pk_fma_f32 v[54:55], v[12:13], v[64:65], v[54:55]
	s_nop 0
	v_mul_f32_e32 v50, 0xbfb8aa3b, v54
	v_exp_f32_e32 v50, v50
	s_nop 0
	v_add_f32_e32 v50, 1.0, v50
	v_rcp_f32_e32 v60, v50
	v_mul_f32_e32 v50, 0xbfb8aa3b, v55
	v_exp_f32_e32 v50, v50
	s_nop 0
	v_add_f32_e32 v50, 1.0, v50
	v_rcp_f32_e32 v61, v50
	s_nop 0
	v_pk_mul_f32 v[54:55], v[54:55], v[60:61]
	s_nop 0
	v_cvt_pk_bf16_f32 v82, v54, v55
	v_pk_fma_f32 v[54:55], v[10:11], v[62:63], v[22:23]
	v_lshlrev_b32_e32 v60, 16, v51
	v_pk_fma_f32 v[54:55], v[18:19], v[52:53], v[54:55]
	v_and_b32_e32 v61, 0xffff0000, v51
	v_pk_fma_f32 v[50:51], v[14:15], v[60:61], v[54:55]
	s_nop 0
	v_mul_f32_e32 v54, 0xbfb8aa3b, v50
	v_mul_f32_e32 v55, 0xbfb8aa3b, v51
	v_exp_f32_e32 v54, v54
	v_exp_f32_e32 v55, v55
	v_add_f32_e32 v54, 1.0, v54
	v_add_f32_e32 v55, 1.0, v55
	v_rcp_f32_e32 v54, v54
	v_rcp_f32_e32 v55, v55
	s_nop 0
	v_pk_mul_f32 v[50:51], v[50:51], v[54:55]
	s_nop 0
	v_cvt_pk_bf16_f32 v83, v50, v51
	v_or_b32_e32 v50, 2, v74
	v_lshlrev_b32_e32 v51, 8, v50
	v_bitop3_b32 v50, v50, v132, 10 bitop3:0x6c
	v_lshlrev_b32_e32 v50, 4, v50
	v_add3_u32 v50, v75, v51, v50
	ds_write_b128 v50, v[80:83]
	v_pk_fma_f32 v[50:51], v[24:25], v[58:59], v[36:37]
	v_lshlrev_b32_e32 v58, 16, v44
	v_pk_fma_f32 v[50:51], v[28:29], v[68:69], v[50:51]
	v_and_b32_e32 v59, 0xffff0000, v44
	v_pk_fma_f32 v[50:51], v[32:33], v[58:59], v[50:51]
	s_nop 0
	v_mul_f32_e32 v44, 0xbfb8aa3b, v50
	v_exp_f32_e32 v44, v44
	s_nop 0
	v_add_f32_e32 v44, 1.0, v44
	v_rcp_f32_e32 v54, v44
	v_mul_f32_e32 v44, 0xbfb8aa3b, v51
	v_exp_f32_e32 v44, v44
	s_nop 0
	v_add_f32_e32 v44, 1.0, v44
	v_rcp_f32_e32 v55, v44
	s_nop 0
	v_pk_mul_f32 v[50:51], v[50:51], v[54:55]
	s_nop 0
	v_cvt_pk_bf16_f32 v44, v50, v51
	v_pk_fma_f32 v[50:51], v[26:27], v[56:57], v[38:39]
	v_lshlrev_b32_e32 v56, 16, v45
	v_pk_fma_f32 v[50:51], v[30:31], v[48:49], v[50:51]
	v_and_b32_e32 v57, 0xffff0000, v45
	v_pk_fma_f32 v[50:51], v[34:35], v[56:57], v[50:51]
	s_nop 0
	v_mul_f32_e32 v45, 0xbfb8aa3b, v50
	v_exp_f32_e32 v45, v45
	s_nop 0
	v_add_f32_e32 v45, 1.0, v45
	v_rcp_f32_e32 v54, v45
	v_mul_f32_e32 v45, 0xbfb8aa3b, v51
	v_exp_f32_e32 v45, v45
	s_nop 0
	v_add_f32_e32 v45, 1.0, v45
	v_rcp_f32_e32 v55, v45
	s_nop 0
	v_pk_mul_f32 v[50:51], v[50:51], v[54:55]
	s_nop 0
	v_cvt_pk_bf16_f32 v45, v50, v51
	v_pk_fma_f32 v[50:51], v[8:9], v[70:71], v[20:21]
	v_lshlrev_b32_e32 v54, 16, v46
	v_pk_fma_f32 v[50:51], v[16:17], v[64:65], v[50:51]
	v_and_b32_e32 v55, 0xffff0000, v46
	v_pk_fma_f32 v[50:51], v[12:13], v[54:55], v[50:51]
	s_nop 0
; __device__ __forceinline__ unsigned cvtpk(float lo, float hi) { f32x2_t v = {lo, hi}; bf16x2_t b = __builtin_convertvector(v, bf16x2_t); return __builtin_bit_cast(unsigned, b); }
; __device__ __forceinline__ float lo16(unsigned u) { return __uint_as_float(u << 16); }
; __device__ __forceinline__ float hi16(unsigned u) { return __uint_as_float(u & 0xffff0000u); }
; __device__ __forceinline__ float silu_fast(float v) { return v * __builtin_amdgcn_rcpf(1.f + __builtin_amdgcn_exp2f(-v * LOG2E)); }
; __device__ __forceinline__ float lo16(unsigned u) { return __uint_as_float(u << 16); }
; template <class Put>
; __device__ __forceinline__ void conv_compute(const ConvRaw& R, const float* cw, const float* cb, int col0, int rg, const Put& put) {
;     const f32x4 w0a = *(const f32x4*)(cw + col0), w0b = *(const f32x4*)(cw + col0 + 4), w1a = *(const f32x4*)(cw + XBCW + col0), w1b = *(const f32x4*)(cw + XBCW + col0 + 4);
;     const f32x4 w2a = *(const f32x4*)(cw + 2 * XBCW + col0), w2b = *(const f32x4*)(cw + 2 * XBCW + col0 + 4), ba = *(const f32x4*)(cb + col0), bb = *(const f32x4*)(cb + col0 + 4);
;     const int r0 = 8 * rg;
; #pragma unroll
;     for (int rr = 0; rr < 8; ++rr) {
;         const u32x4 xm = R.r[rr], x0 = R.r[rr + 1], xp = R.r[rr + 2]; u32x4 o;
; #pragma unroll
;         for (int e = 0; e < 4; ++e) {
;             const float wl0 = e < 2 ? w0a[2 * e] : w0b[2 * e - 4], wh0 = e < 2 ? w0a[2 * e + 1] : w0b[2 * e - 3];
;             const float wl1 = e < 2 ? w1a[2 * e] : w1b[2 * e - 4], wh1 = e < 2 ? w1a[2 * e + 1] : w1b[2 * e - 3];
;             const float wl2 = e < 2 ? w2a[2 * e] : w2b[2 * e - 4], wh2 = e < 2 ? w2a[2 * e + 1] : w2b[2 * e - 3];
;             const float bl = e < 2 ? ba[2 * e] : bb[2 * e - 4], bh = e < 2 ? ba[2 * e + 1] : bb[2 * e - 3];
;             const float vl = bl + wl0 * lo16(xm[e]) + wl1 * lo16(x0[e]) + wl2 * lo16(xp[e]);
;             const float vh = bh + wh0 * hi16(xm[e]) + wh1 * hi16(x0[e]) + wh2 * hi16(xp[e]);
;             o[e] = cvtpk(silu_fast(vl), silu_fast(vh));
;         }
;         put(r0 + rr, o);
;     }
; }
; template <class Wait>
; __device__ __forceinline__ void out_unit(Frame& F, const Ptrs& P, int b, int c, int g, const Wait& wait) {
;     ...
;     conv_compute(R1, P.conv_w, P.conv_b, col1, rg1, PutRow{lds + (mat1 ? L_BROW : L_CIMG), ch1});
	v_mul_f32_e32 v46, 0xbfb8aa3b, v50
	v_exp_f32_e32 v46, v46
	s_nop 0
	v_add_f32_e32 v46, 1.0, v46
	v_rcp_f32_e32 v62, v46
	v_mul_f32_e32 v46, 0xbfb8aa3b, v51
	v_exp_f32_e32 v46, v46
	s_nop 0
	v_add_f32_e32 v46, 1.0, v46
	v_rcp_f32_e32 v63, v46
	s_nop 0
	v_pk_mul_f32 v[50:51], v[50:51], v[62:63]
	s_nop 0
	v_cvt_pk_bf16_f32 v46, v50, v51
	v_pk_fma_f32 v[50:51], v[10:11], v[52:53], v[22:23]
	v_lshlrev_b32_e32 v52, 16, v47
	v_pk_fma_f32 v[50:51], v[18:19], v[60:61], v[50:51]
	v_and_b32_e32 v53, 0xffff0000, v47
	v_pk_fma_f32 v[50:51], v[14:15], v[52:53], v[50:51]
	s_nop 0
	v_mul_f32_e32 v47, 0xbfb8aa3b, v50
	v_exp_f32_e32 v47, v47
	s_nop 0
	v_add_f32_e32 v47, 1.0, v47
	v_rcp_f32_e32 v62, v47
	v_mul_f32_e32 v47, 0xbfb8aa3b, v51
	v_exp_f32_e32 v47, v47
	s_nop 0
	v_add_f32_e32 v47, 1.0, v47
	v_rcp_f32_e32 v63, v47
	s_nop 0
	v_pk_mul_f32 v[50:51], v[50:51], v[62:63]
	s_nop 0
	v_cvt_pk_bf16_f32 v47, v50, v51
	v_or_b32_e32 v50, 3, v74
	v_lshlrev_b32_e32 v51, 8, v50
	v_bitop3_b32 v50, v50, v132, 11 bitop3:0x6c
	v_lshlrev_b32_e32 v50, 4, v50
	v_add3_u32 v50, v75, v51, v50
	ds_write_b128 v50, v[44:47]
	v_pk_fma_f32 v[44:45], v[24:25], v[68:69], v[36:37]
	v_lshlrev_b32_e32 v50, 16, v40
	v_pk_fma_f32 v[44:45], v[28:29], v[58:59], v[44:45]
	v_and_b32_e32 v51, 0xffff0000, v40
	v_pk_fma_f32 v[44:45], v[32:33], v[50:51], v[44:45]
	s_nop 0
	v_mul_f32_e32 v40, 0xbfb8aa3b, v44
	v_exp_f32_e32 v40, v40
	s_nop 0
	v_add_f32_e32 v40, 1.0, v40
	v_rcp_f32_e32 v46, v40
	v_mul_f32_e32 v40, 0xbfb8aa3b, v45
	v_exp_f32_e32 v40, v40
	s_nop 0
	v_add_f32_e32 v40, 1.0, v40
	v_rcp_f32_e32 v47, v40
	s_nop 0
	v_pk_mul_f32 v[44:45], v[44:45], v[46:47]
	s_nop 0
	v_cvt_pk_bf16_f32 v40, v44, v45
	v_pk_fma_f32 v[44:45], v[26:27], v[48:49], v[38:39]
	v_lshlrev_b32_e32 v48, 16, v41
	v_pk_fma_f32 v[44:45], v[30:31], v[56:57], v[44:45]
	v_and_b32_e32 v49, 0xffff0000, v41
	v_pk_fma_f32 v[44:45], v[34:35], v[48:49], v[44:45]
	s_nop 0
	v_mul_f32_e32 v41, 0xbfb8aa3b, v44
	v_exp_f32_e32 v41, v41
	s_nop 0
	v_add_f32_e32 v41, 1.0, v41
	v_rcp_f32_e32 v46, v41
	v_mul_f32_e32 v41, 0xbfb8aa3b, v45
	v_exp_f32_e32 v41, v41
	s_nop 0
	v_add_f32_e32 v41, 1.0, v41
	v_rcp_f32_e32 v47, v41
	s_nop 0
	v_pk_mul_f32 v[44:45], v[44:45], v[46:47]
	s_nop 0
	v_cvt_pk_bf16_f32 v41, v44, v45
	v_pk_fma_f32 v[44:45], v[8:9], v[64:65], v[20:21]
	v_lshlrev_b32_e32 v46, 16, v42
	v_pk_fma_f32 v[44:45], v[16:17], v[54:55], v[44:45]
	v_and_b32_e32 v47, 0xffff0000, v42
	v_pk_fma_f32 v[44:45], v[12:13], v[46:47], v[44:45]
	s_nop 0
	v_mul_f32_e32 v42, 0xbfb8aa3b, v44
	v_exp_f32_e32 v42, v42
	s_nop 0
	v_add_f32_e32 v42, 1.0, v42
	v_rcp_f32_e32 v62, v42
	v_mul_f32_e32 v42, 0xbfb8aa3b, v45
	v_exp_f32_e32 v42, v42
	s_nop 0
	v_add_f32_e32 v42, 1.0, v42
	v_rcp_f32_e32 v63, v42
	s_nop 0
	v_pk_mul_f32 v[44:45], v[44:45], v[62:63]
	s_nop 0
	v_cvt_pk_bf16_f32 v42, v44, v45
	v_pk_fma_f32 v[44:45], v[10:11], v[60:61], v[22:23]
	s_nop 0
	v_pk_fma_f32 v[60:61], v[18:19], v[52:53], v[44:45]
	v_lshlrev_b32_e32 v44, 16, v43
	v_and_b32_e32 v45, 0xffff0000, v43
	v_pk_fma_f32 v[60:61], v[14:15], v[44:45], v[60:61]
	v_pk_fma_f32 v[52:53], v[10:11], v[52:53], v[22:23]
	v_mul_f32_e32 v43, 0xbfb8aa3b, v60
	v_exp_f32_e32 v43, v43
	v_pk_fma_f32 v[52:53], v[18:19], v[44:45], v[52:53]
	v_pk_fma_f32 v[44:45], v[10:11], v[44:45], v[22:23]
	v_add_f32_e32 v43, 1.0, v43
	v_rcp_f32_e32 v62, v43
	v_mul_f32_e32 v43, 0xbfb8aa3b, v61
	v_exp_f32_e32 v43, v43
	s_nop 0
	v_add_f32_e32 v43, 1.0, v43
	v_rcp_f32_e32 v63, v43
	s_nop 0
	v_pk_mul_f32 v[60:61], v[60:61], v[62:63]
	s_nop 0
	v_cvt_pk_bf16_f32 v43, v60, v61
	v_or_b32_e32 v60, 4, v74
	v_lshlrev_b32_e32 v61, 8, v60
	v_bitop3_b32 v60, v60, v132, 12 bitop3:0x6c
	v_lshlrev_b32_e32 v60, 4, v60
	v_add3_u32 v60, v75, v61, v60
	ds_write_b128 v60, v[40:43]
	v_pk_fma_f32 v[40:41], v[24:25], v[58:59], v[36:37]
	v_lshlrev_b32_e32 v42, 16, v4
	v_pk_fma_f32 v[40:41], v[28:29], v[50:51], v[40:41]
	v_and_b32_e32 v43, 0xffff0000, v4
	v_pk_fma_f32 v[40:41], v[32:33], v[42:43], v[40:41]
	v_pk_fma_f32 v[50:51], v[24:25], v[50:51], v[36:37]
	v_mul_f32_e32 v4, 0xbfb8aa3b, v40
	v_exp_f32_e32 v4, v4
	v_pk_fma_f32 v[50:51], v[28:29], v[42:43], v[50:51]
	v_add_f32_e32 v4, 1.0, v4
	v_rcp_f32_e32 v58, v4
	v_mul_f32_e32 v4, 0xbfb8aa3b, v41
	v_exp_f32_e32 v4, v4
	s_nop 0
	v_add_f32_e32 v4, 1.0, v4
	v_rcp_f32_e32 v59, v4
	s_nop 0
	v_pk_mul_f32 v[40:41], v[40:41], v[58:59]
	s_nop 0
	v_cvt_pk_bf16_f32 v58, v40, v41
	v_pk_fma_f32 v[40:41], v[26:27], v[56:57], v[38:39]
	s_nop 0
	v_pk_fma_f32 v[56:57], v[30:31], v[48:49], v[40:41]
	v_lshlrev_b32_e32 v40, 16, v5
	v_and_b32_e32 v41, 0xffff0000, v5
	v_pk_fma_f32 v[4:5], v[34:35], v[40:41], v[56:57]
	v_pk_fma_f32 v[48:49], v[26:27], v[48:49], v[38:39]
	v_mul_f32_e32 v56, 0xbfb8aa3b, v4
	v_mul_f32_e32 v57, 0xbfb8aa3b, v5
	v_exp_f32_e32 v56, v56
	v_exp_f32_e32 v57, v57
	v_pk_fma_f32 v[48:49], v[30:31], v[40:41], v[48:49]
	v_add_f32_e32 v56, 1.0, v56
	v_add_f32_e32 v57, 1.0, v57
	v_rcp_f32_e32 v56, v56
	v_rcp_f32_e32 v57, v57
	s_nop 0
	v_pk_mul_f32 v[4:5], v[4:5], v[56:57]
	s_nop 0
	v_cvt_pk_bf16_f32 v59, v4, v5
	v_pk_fma_f32 v[4:5], v[8:9], v[54:55], v[20:21]
	s_nop 0
	v_pk_fma_f32 v[54:55], v[16:17], v[46:47], v[4:5]
	v_lshlrev_b32_e32 v4, 16, v6
	v_and_b32_e32 v5, 0xffff0000, v6
	v_pk_fma_f32 v[54:55], v[12:13], v[4:5], v[54:55]
	v_pk_fma_f32 v[46:47], v[8:9], v[46:47], v[20:21]
	v_mul_f32_e32 v6, 0xbfb8aa3b, v54
	v_exp_f32_e32 v6, v6
	v_pk_fma_f32 v[46:47], v[16:17], v[4:5], v[46:47]
	v_pk_fma_f32 v[4:5], v[8:9], v[4:5], v[20:21]
	v_add_f32_e32 v6, 1.0, v6
	v_rcp_f32_e32 v56, v6
	v_mul_f32_e32 v6, 0xbfb8aa3b, v55
	v_exp_f32_e32 v6, v6
	s_nop 0
	v_add_f32_e32 v6, 1.0, v6
	v_rcp_f32_e32 v57, v6
; __device__ __forceinline__ unsigned cvtpk(float lo, float hi) { f32x2_t v = {lo, hi}; bf16x2_t b = __builtin_convertvector(v, bf16x2_t); return __builtin_bit_cast(unsigned, b); }
; __device__ __forceinline__ float lo16(unsigned u) { return __uint_as_float(u << 16); }
; __device__ __forceinline__ float hi16(unsigned u) { return __uint_as_float(u & 0xffff0000u); }
; __device__ __forceinline__ float silu_fast(float v) { return v * __builtin_amdgcn_rcpf(1.f + __builtin_amdgcn_exp2f(-v * LOG2E)); }
; template <class Put>
; __device__ __forceinline__ void conv_compute(const ConvRaw& R, const float* cw, const float* cb, int col0, int rg, const Put& put) {
;     const f32x4 w0a = *(const f32x4*)(cw + col0), w0b = *(const f32x4*)(cw + col0 + 4), w1a = *(const f32x4*)(cw + XBCW + col0), w1b = *(const f32x4*)(cw + XBCW + col0 + 4);
;     const f32x4 w2a = *(const f32x4*)(cw + 2 * XBCW + col0), w2b = *(const f32x4*)(cw + 2 * XBCW + col0 + 4), ba = *(const f32x4*)(cb + col0), bb = *(const f32x4*)(cb + col0 + 4);
;     const int r0 = 8 * rg;
; #pragma unroll
;     for (int rr = 0; rr < 8; ++rr) {
;         const u32x4 xm = R.r[rr], x0 = R.r[rr + 1], xp = R.r[rr + 2]; u32x4 o;
; #pragma unroll
;         for (int e = 0; e < 4; ++e) {
;             const float wl0 = e < 2 ? w0a[2 * e] : w0b[2 * e - 4], wh0 = e < 2 ? w0a[2 * e + 1] : w0b[2 * e - 3];
;             const float wl1 = e < 2 ? w1a[2 * e] : w1b[2 * e - 4], wh1 = e < 2 ? w1a[2 * e + 1] : w1b[2 * e - 3];
;             const float wl2 = e < 2 ? w2a[2 * e] : w2b[2 * e - 4], wh2 = e < 2 ? w2a[2 * e + 1] : w2b[2 * e - 3];
;             const float bl = e < 2 ? ba[2 * e] : bb[2 * e - 4], bh = e < 2 ? ba[2 * e + 1] : bb[2 * e - 3];
;             const float vl = bl + wl0 * lo16(xm[e]) + wl1 * lo16(x0[e]) + wl2 * lo16(xp[e]);
;             const float vh = bh + wh0 * hi16(xm[e]) + wh1 * hi16(x0[e]) + wh2 * hi16(xp[e]);
;             o[e] = cvtpk(silu_fast(vl), silu_fast(vh));
;         }
;         put(r0 + rr, o);
;     }
; }
; template <class Wait>
; __device__ __forceinline__ void out_unit(Frame& F, const Ptrs& P, int b, int c, int g, const Wait& wait) {
;     ...
;     conv_compute(R1, P.conv_w, P.conv_b, col1, rg1, PutRow{lds + (mat1 ? L_BROW : L_CIMG), ch1});
;     __syncthreads();
;     ConvRaw R2;
;     conv_load(R2, XBC, b, c, col2, rg2);
	v_lshlrev_b32_e32 v6, 16, v7
	v_and_b32_e32 v7, 0xffff0000, v7
	v_pk_fma_f32 v[52:53], v[14:15], v[6:7], v[52:53]
	v_pk_mul_f32 v[54:55], v[54:55], v[56:57]
	v_pk_fma_f32 v[44:45], v[18:19], v[6:7], v[44:45]
	v_cvt_pk_bf16_f32 v60, v54, v55
	v_mul_f32_e32 v54, 0xbfb8aa3b, v52
	v_mul_f32_e32 v55, 0xbfb8aa3b, v53
	v_exp_f32_e32 v54, v54
	v_exp_f32_e32 v55, v55
	v_add_f32_e32 v54, 1.0, v54
	v_add_f32_e32 v55, 1.0, v55
	v_rcp_f32_e32 v54, v54
	v_rcp_f32_e32 v55, v55
	s_nop 0
	v_pk_mul_f32 v[52:53], v[52:53], v[54:55]
	s_nop 0
	v_cvt_pk_bf16_f32 v61, v52, v53
	v_or_b32_e32 v52, 5, v74
	v_lshlrev_b32_e32 v53, 8, v52
	v_bitop3_b32 v52, v52, v132, 13 bitop3:0x6c
	v_lshlrev_b32_e32 v52, 4, v52
	v_add3_u32 v52, v75, v53, v52
	ds_write_b128 v52, v[58:61]
	v_lshlrev_b32_e32 v52, 16, v0
	v_and_b32_e32 v53, 0xffff0000, v0
	v_pk_fma_f32 v[50:51], v[32:33], v[52:53], v[50:51]
	s_nop 0
	v_mul_f32_e32 v0, 0xbfb8aa3b, v50
	v_exp_f32_e32 v0, v0
	s_nop 0
	v_add_f32_e32 v0, 1.0, v0
	v_rcp_f32_e32 v54, v0
	v_mul_f32_e32 v0, 0xbfb8aa3b, v51
	v_exp_f32_e32 v0, v0
	s_nop 0
	v_add_f32_e32 v0, 1.0, v0
	v_rcp_f32_e32 v55, v0
	s_nop 0
	v_pk_mul_f32 v[50:51], v[50:51], v[54:55]
	s_nop 0
	v_cvt_pk_bf16_f32 v0, v50, v51
	v_lshlrev_b32_e32 v50, 16, v1
	v_and_b32_e32 v51, 0xffff0000, v1
	v_pk_fma_f32 v[48:49], v[34:35], v[50:51], v[48:49]
	s_nop 0
	v_mul_f32_e32 v1, 0xbfb8aa3b, v48
	v_exp_f32_e32 v1, v1
	s_nop 0
	v_add_f32_e32 v1, 1.0, v1
	v_rcp_f32_e32 v54, v1
	v_mul_f32_e32 v1, 0xbfb8aa3b, v49
	v_exp_f32_e32 v1, v1
	s_nop 0
	v_add_f32_e32 v1, 1.0, v1
	v_rcp_f32_e32 v55, v1
	s_nop 0
	v_pk_mul_f32 v[48:49], v[48:49], v[54:55]
	s_nop 0
	v_cvt_pk_bf16_f32 v1, v48, v49
	v_lshlrev_b32_e32 v48, 16, v2
	v_and_b32_e32 v49, 0xffff0000, v2
	v_pk_fma_f32 v[46:47], v[12:13], v[48:49], v[46:47]
	v_pk_fma_f32 v[4:5], v[16:17], v[48:49], v[4:5]
	v_mul_f32_e32 v2, 0xbfb8aa3b, v46
	v_exp_f32_e32 v2, v2
	s_nop 0
	v_add_f32_e32 v2, 1.0, v2
	v_rcp_f32_e32 v54, v2
	v_mul_f32_e32 v2, 0xbfb8aa3b, v47
	v_exp_f32_e32 v2, v2
	s_nop 0
	v_add_f32_e32 v2, 1.0, v2
	v_rcp_f32_e32 v55, v2
	s_nop 0
	v_pk_mul_f32 v[46:47], v[46:47], v[54:55]
	s_nop 0
	v_cvt_pk_bf16_f32 v2, v46, v47
	v_lshlrev_b32_e32 v46, 16, v3
	v_and_b32_e32 v47, 0xffff0000, v3
	v_pk_fma_f32 v[44:45], v[14:15], v[46:47], v[44:45]
	s_nop 0
	v_mul_f32_e32 v3, 0xbfb8aa3b, v44
	v_exp_f32_e32 v3, v3
	s_nop 0
	v_add_f32_e32 v3, 1.0, v3
	v_rcp_f32_e32 v54, v3
	v_mul_f32_e32 v3, 0xbfb8aa3b, v45
	v_exp_f32_e32 v3, v3
	s_nop 0
	v_add_f32_e32 v3, 1.0, v3
	v_rcp_f32_e32 v55, v3
	s_nop 0
	v_pk_mul_f32 v[44:45], v[44:45], v[54:55]
	s_nop 0
	v_cvt_pk_bf16_f32 v3, v44, v45
	v_or_b32_e32 v44, 6, v74
	v_lshlrev_b32_e32 v45, 8, v44
	v_bitop3_b32 v44, v44, v132, 14 bitop3:0x6c
	v_lshlrev_b32_e32 v44, 4, v44
	v_add3_u32 v44, v75, v45, v44
	ds_write_b128 v44, v[0:3]
	v_pk_fma_f32 v[2:3], v[24:25], v[42:43], v[36:37]
	v_lshlrev_b32_e32 v0, 16, v79
	v_and_b32_e32 v1, 0xffff0000, v79
	v_pk_fma_f32 v[2:3], v[28:29], v[52:53], v[2:3]
	v_pk_fma_f32 v[24:25], v[26:27], v[40:41], v[38:39]
	v_pk_fma_f32 v[0:1], v[32:33], v[0:1], v[2:3]
	v_pk_fma_f32 v[24:25], v[30:31], v[50:51], v[24:25]
	v_mul_f32_e32 v2, 0xbfb8aa3b, v0
	v_mul_f32_e32 v3, 0xbfb8aa3b, v1
	v_exp_f32_e32 v2, v2
	v_exp_f32_e32 v3, v3
	v_add_f32_e32 v2, 1.0, v2
	v_add_f32_e32 v3, 1.0, v3
	v_rcp_f32_e32 v2, v2
	v_rcp_f32_e32 v3, v3
	s_nop 0
	v_pk_mul_f32 v[0:1], v[0:1], v[2:3]
	v_lshlrev_b32_e32 v2, 16, v78
	v_and_b32_e32 v3, 0xffff0000, v78
	v_pk_fma_f32 v[2:3], v[34:35], v[2:3], v[24:25]
	v_cvt_pk_bf16_f32 v0, v0, v1
	v_mul_f32_e32 v1, 0xbfb8aa3b, v2
	v_exp_f32_e32 v1, v1
	s_nop 0
	v_add_f32_e32 v1, 1.0, v1
	v_rcp_f32_e32 v24, v1
	v_mul_f32_e32 v1, 0xbfb8aa3b, v3
	v_exp_f32_e32 v1, v1
	s_nop 0
	v_add_f32_e32 v1, 1.0, v1
	v_rcp_f32_e32 v25, v1
	s_nop 0
	v_pk_mul_f32 v[2:3], v[2:3], v[24:25]
	s_nop 0
	v_cvt_pk_bf16_f32 v1, v2, v3
	v_lshlrev_b32_e32 v2, 16, v77
	v_and_b32_e32 v3, 0xffff0000, v77
	v_pk_fma_f32 v[2:3], v[12:13], v[2:3], v[4:5]
	s_nop 0
	v_mul_f32_e32 v4, 0xbfb8aa3b, v2
	v_mul_f32_e32 v5, 0xbfb8aa3b, v3
	v_exp_f32_e32 v4, v4
	v_exp_f32_e32 v5, v5
	v_add_f32_e32 v4, 1.0, v4
	v_add_f32_e32 v5, 1.0, v5
	v_rcp_f32_e32 v4, v4
	v_rcp_f32_e32 v5, v5
	s_nop 0
	v_pk_mul_f32 v[2:3], v[2:3], v[4:5]
	v_pk_fma_f32 v[4:5], v[10:11], v[6:7], v[22:23]
	v_lshlrev_b32_e32 v6, 16, v76
	v_pk_fma_f32 v[4:5], v[18:19], v[46:47], v[4:5]
	v_and_b32_e32 v7, 0xffff0000, v76
	v_pk_fma_f32 v[4:5], v[14:15], v[6:7], v[4:5]
	v_cvt_pk_bf16_f32 v2, v2, v3
	v_mul_f32_e32 v3, 0xbfb8aa3b, v4
	v_exp_f32_e32 v3, v3
	s_nop 0
	v_add_f32_e32 v3, 1.0, v3
	v_rcp_f32_e32 v6, v3
	v_mul_f32_e32 v3, 0xbfb8aa3b, v5
	v_exp_f32_e32 v3, v3
	s_nop 0
	v_add_f32_e32 v3, 1.0, v3
	v_rcp_f32_e32 v7, v3
	s_nop 0
	v_pk_mul_f32 v[4:5], v[4:5], v[6:7]
	s_nop 0
	v_cvt_pk_bf16_f32 v3, v4, v5
	v_bitop3_b32 v5, v74, v224, 7 bitop3:0x36
	v_or_b32_e32 v4, 7, v74
	v_lshlrev_b32_e32 v5, 4, v5
	v_lshlrev_b32_e32 v4, 8, v4
	v_and_b32_e32 v5, 0xf0, v5
	v_add3_u32 v4, v75, v4, v5
	ds_write_b128 v4, v[0:3]
	v_max_i32_e32 v2, 0, v143
	v_mov_b32_e32 v3, v201
	v_lshl_add_u64 v[0:1], v[130:131], 1, s[14:15]
	v_lshl_add_u64 v[2:3], s[42:43], 0, v[2:3]
	v_mad_u64_u32 v[4:5], s[0:1], v2, s87, v[0:1]
	v_or_b32_e32 v2, s42, v144
	v_mad_i32_i24 v5, v3, s87, v5
	v_mad_u64_u32 v[2:3], s[0:1], v2, s87, v[0:1]
	v_mad_i32_i24 v3, s43, v203, v3
	s_waitcnt lgkmcnt(0)
	s_barrier
; #define LAS __attribute__((address_space(3)))
; template <class Wait>
; __device__ __forceinline__ void out_unit(Frame& F, const Ptrs& P, int b, int c, int g, const Wait& wait) {
;     ...
;     ConvRaw R2;
;     conv_load(R2, XBC, b, c, col2, rg2);
;     {
;         const int sblk = wid >> 1, s = 32 * sblk + r32;
;         f32x16 d0 = f32x16{}, d1 = f32x16{};
;         const int q0 = 64 * (wid & 1) + r32, q1 = q0 + 32;
; #pragma unroll
;         for (int ks = 0; ks < 8; ++ks) { const int chn = 2 * ks + hi;
;             const bf16x8 a = *(const LAS bf16x8*)(lds + L_BROW + s * 256 + ((chn ^ (s & 15)) * 16));
;             const bf16x8 c0 = *(const LAS bf16x8*)(lds + L_CIMG + q0 * 256 + ((chn ^ (q0 & 15)) * 16)), c1 = *(const LAS bf16x8*)(lds + L_CIMG + q1 * 256 + ((chn ^ (q1 & 15)) * 16));
;             d0 = __builtin_amdgcn_mfma_f32_32x32x16_bf16(a, c0, d0, 0, 0, 0); d1 = __builtin_amdgcn_mfma_f32_32x32x16_bf16(a, c1, d1, 0, 0, 0); }
	global_load_dwordx4 v[68:71], v[4:5], off nt
	global_load_dwordx4 v[60:63], v[2:3], off nt
	v_add_u32_e32 v2, 2, v143
	v_mov_b32_e32 v3, v201
	v_lshl_add_u64 v[2:3], s[42:43], 0, v[2:3]
	v_mad_u64_u32 v[4:5], s[0:1], v2, s87, v[0:1]
	v_mad_i32_i24 v5, v3, s87, v5
	v_add_u32_e32 v2, 3, v143
	v_mov_b32_e32 v3, v201
	v_lshl_add_u64 v[2:3], s[42:43], 0, v[2:3]
	global_load_dwordx4 v[56:59], v[4:5], off nt
	v_mad_u64_u32 v[4:5], s[0:1], v2, s87, v[0:1]
	v_mad_i32_i24 v5, v3, s87, v5
	v_add_u32_e32 v2, 4, v143
	v_mov_b32_e32 v3, v201
	v_lshl_add_u64 v[2:3], s[42:43], 0, v[2:3]
	global_load_dwordx4 v[52:55], v[4:5], off nt
	v_mad_u64_u32 v[4:5], s[0:1], v2, s87, v[0:1]
	v_mad_i32_i24 v5, v3, s87, v5
	v_add_u32_e32 v2, 5, v143
	v_mov_b32_e32 v3, v201
	v_lshl_add_u64 v[2:3], s[42:43], 0, v[2:3]
	global_load_dwordx4 v[48:51], v[4:5], off nt
	v_mad_u64_u32 v[4:5], s[0:1], v2, s87, v[0:1]
	v_mad_i32_i24 v5, v3, s87, v5
	v_add_u32_e32 v2, 6, v143
	v_mov_b32_e32 v3, v201
	v_lshl_add_u64 v[2:3], s[42:43], 0, v[2:3]
	global_load_dwordx4 v[44:47], v[4:5], off nt
	v_mad_u64_u32 v[4:5], s[0:1], v2, s87, v[0:1]
	v_mad_i32_i24 v5, v3, s87, v5
	v_add_u32_e32 v2, 7, v143
	v_mov_b32_e32 v3, v201
	v_lshl_add_u64 v[2:3], s[42:43], 0, v[2:3]
	global_load_dwordx4 v[40:43], v[4:5], off nt
	v_mad_u64_u32 v[4:5], s[0:1], v2, s87, v[0:1]
	v_mad_i32_i24 v5, v3, s87, v5
	v_add_u32_e32 v2, 8, v143
	v_mov_b32_e32 v3, v201
	v_lshl_add_u64 v[2:3], s[42:43], 0, v[2:3]
	global_load_dwordx4 v[36:39], v[4:5], off nt
	v_mad_u64_u32 v[4:5], s[0:1], v2, s87, v[0:1]
	v_add_u32_e32 v2, 9, v143
	v_min_u32_e32 v2, 0x1fff, v2
	v_or_b32_e32 v2, s42, v2
	v_mad_u64_u32 v[0:1], s[0:1], v2, s87, v[0:1]
	v_mad_i32_i24 v5, v3, s87, v5
	v_mad_i32_i24 v1, s43, v203, v1
	global_load_dwordx4 v[32:35], v[4:5], off nt
	global_load_dwordx4 v[64:67], v[0:1], off nt
	v_xor_b32_e32 v0, v223, v132
	v_lshlrev_b32_e32 v123, 4, v0
	v_add_u32_e32 v0, v73, v123
	ds_read_b128 v[0:3], v0
	v_add_u32_e32 v4, v86, v123
	v_add_u32_e32 v8, v87, v123
	ds_read_b128 v[4:7], v4
	ds_read_b128 v[8:11], v8
	v_bitop3_b32 v74, v223, v132, 2 bitop3:0x36
	v_lshlrev_b32_e32 v124, 4, v74
	v_add_u32_e32 v74, v73, v124
	ds_read_b128 v[74:77], v74
	s_waitcnt lgkmcnt(2)
	v_mfma_f32_32x32x16_bf16 v[16:31], v[0:3], v[4:7], 0
	v_add_u32_e32 v78, v86, v124
	v_add_u32_e32 v82, v87, v124
	ds_read_b128 v[78:81], v78
	ds_read_b128 v[82:85], v82
	s_and_b64 s[0:1], s[48:49], vcc
	v_cmp_ne_u32_e32 vcc, 0, v72
	s_waitcnt vmcnt(0)
	v_cndmask_b32_e64 v72, v67, 0, s[0:1]
	s_waitcnt lgkmcnt(3)
	v_mfma_f32_32x32x16_bf16 v[0:15], v[0:3], v[8:11], 0
	v_cndmask_b32_e32 v68, 0, v68, vcc
	v_and_b32_e32 v67, 0xffff0000, v60
	s_waitcnt lgkmcnt(1)
	v_mfma_f32_32x32x16_bf16 v[16:31], v[74:77], v[78:81], v[16:31]
	s_waitcnt lgkmcnt(0)
	v_mfma_f32_32x32x16_bf16 v[0:15], v[74:77], v[82:85], v[0:15]
	v_bitop3_b32 v74, v223, v132, 4 bitop3:0x36
	v_lshlrev_b32_e32 v125, 4, v74
	v_add_u32_e32 v74, v73, v125
	ds_read_b128 v[74:77], v74
	v_add_u32_e32 v78, v86, v125
	v_add_u32_e32 v82, v87, v125
	ds_read_b128 v[78:81], v78
	ds_read_b128 v[82:85], v82
	s_waitcnt lgkmcnt(1)
	v_mfma_f32_32x32x16_bf16 v[16:31], v[74:77], v[78:81], v[16:31]
	s_waitcnt lgkmcnt(0)
	v_mfma_f32_32x32x16_bf16 v[0:15], v[74:77], v[82:85], v[0:15]
	v_bitop3_b32 v74, v223, v132, 6 bitop3:0x36
	v_lshlrev_b32_e32 v126, 4, v74
	v_add_u32_e32 v74, v73, v126
	ds_read_b128 v[74:77], v74
	v_add_u32_e32 v78, v86, v126
	v_add_u32_e32 v82, v87, v126
	ds_read_b128 v[78:81], v78
	ds_read_b128 v[82:85], v82
	s_waitcnt lgkmcnt(1)
	v_mfma_f32_32x32x16_bf16 v[16:31], v[74:77], v[78:81], v[16:31]
	s_waitcnt lgkmcnt(0)
	v_mfma_f32_32x32x16_bf16 v[0:15], v[74:77], v[82:85], v[0:15]
	v_bitop3_b32 v74, v223, v132, 8 bitop3:0x36
	v_lshlrev_b32_e32 v127, 4, v74
	v_add_u32_e32 v74, v73, v127
	ds_read_b128 v[74:77], v74
	v_add_u32_e32 v78, v86, v127
	v_add_u32_e32 v82, v87, v127
	ds_read_b128 v[78:81], v78
	ds_read_b128 v[82:85], v82
	s_waitcnt lgkmcnt(1)
	v_mfma_f32_32x32x16_bf16 v[16:31], v[74:77], v[78:81], v[16:31]
	s_waitcnt lgkmcnt(0)
	v_mfma_f32_32x32x16_bf16 v[0:15], v[74:77], v[82:85], v[0:15]
	v_bitop3_b32 v74, v223, v132, 10 bitop3:0x36
	v_lshlrev_b32_e32 v133, 4, v74
	v_add_u32_e32 v74, v73, v133
	ds_read_b128 v[74:77], v74
	v_add_u32_e32 v78, v86, v133
	v_add_u32_e32 v82, v87, v133
	ds_read_b128 v[78:81], v78
	ds_read_b128 v[82:85], v82
	s_waitcnt lgkmcnt(1)
	v_mfma_f32_32x32x16_bf16 v[16:31], v[74:77], v[78:81], v[16:31]
	s_waitcnt lgkmcnt(0)
	v_mfma_f32_32x32x16_bf16 v[0:15], v[74:77], v[82:85], v[0:15]
	v_bitop3_b32 v74, v223, v132, 12 bitop3:0x36
	v_lshlrev_b32_e32 v134, 4, v74
	v_add_u32_e32 v74, v73, v134
	ds_read_b128 v[74:77], v74
	v_add_u32_e32 v78, v86, v134
	v_add_u32_e32 v82, v87, v134
	ds_read_b128 v[78:81], v78
	ds_read_b128 v[82:85], v82
	s_waitcnt lgkmcnt(1)
	v_mfma_f32_32x32x16_bf16 v[16:31], v[74:77], v[78:81], v[16:31]
	s_waitcnt lgkmcnt(0)
	v_mfma_f32_32x32x16_bf16 v[0:15], v[74:77], v[82:85], v[0:15]
	v_bitop3_b32 v74, v223, v132, 14 bitop3:0x36
	v_lshlrev_b32_e32 v135, 4, v74
	v_add_u32_e32 v73, v73, v135
	ds_read_b128 v[74:77], v73
	v_add_u32_e32 v73, v86, v135
	ds_read_b128 v[78:81], v73
	v_add_u32_e32 v73, v87, v135
	ds_read_b128 v[82:85], v73
	s_waitcnt lgkmcnt(0)
; #define LAS __attribute__((address_space(3)))
; __device__ __forceinline__ float lo16(unsigned u) { return __uint_as_float(u << 16); }
; template <class Put>
; __device__ __forceinline__ void conv_compute(const ConvRaw& R, const float* cw, const float* cb, int col0, int rg, const Put& put) {
;     const f32x4 w0a = *(const f32x4*)(cw + col0), w0b = *(const f32x4*)(cw + col0 + 4), w1a = *(const f32x4*)(cw + XBCW + col0), w1b = *(const f32x4*)(cw + XBCW + col0 + 4);
;     const f32x4 w2a = *(const f32x4*)(cw + 2 * XBCW + col0), w2b = *(const f32x4*)(cw + 2 * XBCW + col0 + 4), ba = *(const f32x4*)(cb + col0), bb = *(const f32x4*)(cb + col0 + 4);
;     const int r0 = 8 * rg;
; #pragma unroll
;     for (int rr = 0; rr < 8; ++rr) {
;         const u32x4 xm = R.r[rr], x0 = R.r[rr + 1], xp = R.r[rr + 2]; u32x4 o;
; #pragma unroll
;         for (int e = 0; e < 4; ++e) {
;             const float wl0 = e < 2 ? w0a[2 * e] : w0b[2 * e - 4], wh0 = e < 2 ? w0a[2 * e + 1] : w0b[2 * e - 3];
;             const float wl1 = e < 2 ? w1a[2 * e] : w1b[2 * e - 4], wh1 = e < 2 ? w1a[2 * e + 1] : w1b[2 * e - 3];
;             const float wl2 = e < 2 ? w2a[2 * e] : w2b[2 * e - 4], wh2 = e < 2 ? w2a[2 * e + 1] : w2b[2 * e - 3];
;             const float bl = e < 2 ? ba[2 * e] : bb[2 * e - 4], bh = e < 2 ? ba[2 * e + 1] : bb[2 * e - 3];
;             const float vl = bl + wl0 * lo16(xm[e]) + wl1 * lo16(x0[e]) + wl2 * lo16(xp[e]);
;             const float vh = bh + wh0 * hi16(xm[e]) + wh1 * hi16(x0[e]) + wh2 * hi16(xp[e]);
;             o[e] = cvtpk(silu_fast(vl), silu_fast(vh));
; template <class Wait>
; __device__ __forceinline__ void out_unit(Frame& F, const Ptrs& P, int b, int c, int g, const Wait& wait) {
;     ...
; #pragma unroll
;         for (int g4 = 0; g4 < 4; ++g4) { const int chs = 4 * sblk + g4;
;             u32x2 w0; w0.x = cvtpk(d0[4 * g4], d0[4 * g4 + 1]); w0.y = cvtpk(d0[4 * g4 + 2], d0[4 * g4 + 3]);
;             u32x2 w1; w1.x = cvtpk(d1[4 * g4], d1[4 * g4 + 1]); w1.y = cvtpk(d1[4 * g4 + 2], d1[4 * g4 + 3]);
;             *(LAS u32x2*)(lds + L_CB + q0 * 256 + ((chs ^ (q0 & 15)) * 16) + hi * 8) = w0; *(LAS u32x2*)(lds + L_CB + q1 * 256 + ((chs ^ (q1 & 15)) * 16) + hi * 8) = w1; }
;     }
;     __syncthreads();
;     conv_compute(R2, P.conv_w, P.conv_b, col2, rg2, PutTr{lds + L_XS + hl2 * 16384, ch2});
	v_mfma_f32_32x32x16_bf16 v[0:15], v[74:77], v[82:85], v[0:15]
	v_cndmask_b32_e64 v73, v66, 0, s[0:1]
	v_lshrrev_b32_e32 v66, 1, v141
	v_lshlrev_b32_e32 v82, 16, v62
	v_and_b32_e32 v83, 0xffff0000, v62
	v_lshlrev_b32_e32 v62, 16, v63
	v_and_b32_e32 v63, 0xffff0000, v63
	s_nop 5
	v_cvt_pk_bf16_f32 v0, v0, v1
	v_mfma_f32_32x32x16_bf16 v[16:31], v[74:77], v[78:81], v[16:31]
	v_cvt_pk_bf16_f32 v1, v2, v3
	v_xor_b32_e32 v2, s71, v132
	v_cndmask_b32_e32 v78, 0, v70, vcc
	v_cndmask_b32_e32 v79, 0, v69, vcc
	v_add_u32_e32 v69, v86, v204
	v_add_u32_e32 v70, v87, v204
	v_lshlrev_b32_e32 v2, 4, v2
	v_add_u32_e32 v3, v69, v2
	v_add_u32_e32 v2, v70, v2
	ds_write_b64 v2, v[0:1] offset:32768
	v_cvt_pk_bf16_f32 v2, v4, v5
	v_xor_b32_e32 v4, s78, v132
	v_lshlrev_b32_e32 v4, 4, v4
	v_cvt_pk_bf16_f32 v0, v20, v21
	v_cvt_pk_bf16_f32 v1, v22, v23
	v_add_u32_e32 v5, v69, v4
	v_cvt_pk_bf16_f32 v16, v16, v17
	v_cvt_pk_bf16_f32 v17, v18, v19
	ds_write_b64 v5, v[0:1] offset:32768
	v_add_u32_e32 v0, v70, v4
	v_xor_b32_e32 v4, s79, v132
	ds_write_b64 v3, v[16:17] offset:32768
	v_cvt_pk_bf16_f32 v3, v6, v7
	v_lshlrev_b32_e32 v4, 4, v4
	ds_write_b64 v0, v[2:3] offset:32768
	v_cvt_pk_bf16_f32 v0, v24, v25
	v_cvt_pk_bf16_f32 v1, v26, v27
	v_add_u32_e32 v5, v69, v4
	ds_write_b64 v5, v[0:1] offset:32768
	v_add_u32_e32 v0, v70, v4
	v_xor_b32_e32 v4, s80, v132
	v_cvt_pk_bf16_f32 v2, v8, v9
	v_cvt_pk_bf16_f32 v3, v10, v11
	v_lshlrev_b32_e32 v4, 4, v4
	ds_write_b64 v0, v[2:3] offset:32768
	v_cvt_pk_bf16_f32 v0, v28, v29
	v_cvt_pk_bf16_f32 v1, v30, v31
	v_cvt_pk_bf16_f32 v2, v12, v13
	v_add_u32_e32 v5, v69, v4
	v_lshlrev_b64 v[12:13], 2, v[130:131]
	v_cvt_pk_bf16_f32 v3, v14, v15
	ds_write_b64 v5, v[0:1] offset:32768
	v_add_u32_e32 v0, v70, v4
	v_lshl_add_u64 v[4:5], s[24:25], 0, v[12:13]
	ds_write_b64 v0, v[2:3] offset:32768
	s_waitcnt lgkmcnt(0)
	s_barrier
	global_load_dwordx4 v[0:3], v[4:5], off offset:16 nt
	global_load_dwordx4 v[16:19], v[4:5], off nt
	v_lshl_add_u64 v[4:5], s[30:31], 0, v[12:13]
	v_lshl_add_u64 v[14:15], s[36:37], 0, v[12:13]
	v_lshl_add_u64 v[28:29], s[26:27], 0, v[12:13]
	global_load_dwordx4 v[8:11], v[4:5], off offset:16 nt
	global_load_dwordx4 v[20:23], v[4:5], off nt
	s_nop 0
	global_load_dwordx4 v[4:7], v[14:15], off offset:16 nt
	global_load_dwordx4 v[24:27], v[14:15], off nt
	s_nop 0
	global_load_dwordx4 v[12:15], v[28:29], off offset:16 nt
	s_nop 0
	global_load_dwordx4 v[28:31], v[28:29], off nt
	v_cndmask_b32_e64 v74, v65, 0, s[0:1]
	v_lshlrev_b32_e32 v65, 1, v140
	v_and_or_b32 v65, v65, 8, v66
	v_cndmask_b32_e64 v76, v64, 0, s[0:1]
	v_lshlrev_b32_e32 v64, 14, v142
	v_lshlrev_b32_e32 v65, 10, v65
	v_add3_u32 v64, s69, v64, v65
	v_lshlrev_b32_e32 v65, 9, v141
	v_lshlrev_b32_e32 v66, 4, v140
	v_and_b32_e32 v65, 0x200, v65
	v_and_b32_e32 v66, 48, v66
	v_add3_u32 v75, v64, v65, v66
	v_lshlrev_b32_e32 v64, 16, v68
	v_and_b32_e32 v65, 0xffff0000, v68
	v_lshlrev_b32_e32 v66, 16, v60
	v_cndmask_b32_e32 v77, 0, v71, vcc
	v_lshlrev_b32_e32 v80, 16, v61
	v_and_b32_e32 v81, 0xffff0000, v61
	v_readlane_b32 s0, v252, 11
	v_readlane_b32 s1, v252, 12
	s_andn2_b64 vcc, exec, s[0:1]
	s_waitcnt vmcnt(0)
	v_pk_fma_f32 v[64:65], v[16:17], v[64:65], v[28:29]
	s_nop 0
	v_pk_fma_f32 v[68:69], v[20:21], v[66:67], v[64:65]
	v_lshlrev_b32_e32 v64, 16, v56
	v_and_b32_e32 v65, 0xffff0000, v56
	v_pk_fma_f32 v[68:69], v[24:25], v[64:65], v[68:69]
	v_pk_fma_f32 v[66:67], v[16:17], v[66:67], v[28:29]
	v_mul_f32_e32 v56, 0xbfb8aa3b, v68
	v_exp_f32_e32 v56, v56
	v_pk_fma_f32 v[66:67], v[20:21], v[64:65], v[66:67]
	v_add_f32_e32 v56, 1.0, v56
	v_rcp_f32_e32 v70, v56
	v_mul_f32_e32 v56, 0xbfb8aa3b, v69
	v_exp_f32_e32 v56, v56
	s_nop 0
	v_add_f32_e32 v56, 1.0, v56
	v_rcp_f32_e32 v71, v56
	v_lshlrev_b32_e32 v56, 16, v57
	v_and_b32_e32 v57, 0xffff0000, v57
	v_pk_mul_f32 v[68:69], v[68:69], v[70:71]
	v_lshlrev_b32_e32 v70, 16, v79
	v_and_b32_e32 v71, 0xffff0000, v79
	v_pk_fma_f32 v[70:71], v[18:19], v[70:71], v[30:31]
	v_cvt_pk_bf16_f32 v68, v68, v69
	v_pk_fma_f32 v[60:61], v[22:23], v[80:81], v[70:71]
	s_nop 0
	v_pk_fma_f32 v[60:61], v[26:27], v[56:57], v[60:61]
	s_nop 0
	v_mul_f32_e32 v69, 0xbfb8aa3b, v60
	v_exp_f32_e32 v69, v69
	s_nop 0
	v_add_f32_e32 v69, 1.0, v69
	v_rcp_f32_e32 v70, v69
	v_mul_f32_e32 v69, 0xbfb8aa3b, v61
	v_exp_f32_e32 v69, v69
	s_nop 0
	v_add_f32_e32 v69, 1.0, v69
	v_rcp_f32_e32 v71, v69
	s_nop 0
	v_pk_mul_f32 v[60:61], v[60:61], v[70:71]
	s_nop 0
	v_cvt_pk_bf16_f32 v69, v60, v61
	v_lshlrev_b32_e32 v60, 16, v78
	v_and_b32_e32 v61, 0xffff0000, v78
	v_pk_fma_f32 v[60:61], v[0:1], v[60:61], v[12:13]
	s_nop 0
	v_pk_fma_f32 v[70:71], v[8:9], v[82:83], v[60:61]
	v_lshlrev_b32_e32 v60, 16, v58
	v_and_b32_e32 v61, 0xffff0000, v58
	v_pk_fma_f32 v[70:71], v[4:5], v[60:61], v[70:71]
	s_nop 0
	v_mul_f32_e32 v58, 0xbfb8aa3b, v70
	v_exp_f32_e32 v58, v58
	s_nop 0
	v_add_f32_e32 v58, 1.0, v58
	v_rcp_f32_e32 v78, v58
	v_mul_f32_e32 v58, 0xbfb8aa3b, v71
	v_exp_f32_e32 v58, v58
	s_nop 0
	v_add_f32_e32 v58, 1.0, v58
	v_rcp_f32_e32 v79, v58
	v_lshlrev_b32_e32 v58, 16, v59
	v_and_b32_e32 v59, 0xffff0000, v59
	v_pk_mul_f32 v[70:71], v[70:71], v[78:79]
	v_lshlrev_b32_e32 v78, 16, v77
	v_and_b32_e32 v79, 0xffff0000, v77
	v_pk_fma_f32 v[78:79], v[2:3], v[78:79], v[14:15]
	v_cvt_pk_bf16_f32 v70, v70, v71
	v_pk_fma_f32 v[78:79], v[10:11], v[62:63], v[78:79]
	s_nop 0
	v_pk_fma_f32 v[78:79], v[6:7], v[58:59], v[78:79]
	s_nop 0
	v_mul_f32_e32 v71, 0xbfb8aa3b, v78
	v_exp_f32_e32 v71, v71
	s_nop 0
	v_add_f32_e32 v71, 1.0, v71
	v_rcp_f32_e32 v84, v71
	v_mul_f32_e32 v71, 0xbfb8aa3b, v79
	v_exp_f32_e32 v71, v71
	s_nop 0
	v_add_f32_e32 v71, 1.0, v71
	v_rcp_f32_e32 v85, v71
	s_nop 0
; __device__ __forceinline__ unsigned cvtpk(float lo, float hi) { f32x2_t v = {lo, hi}; bf16x2_t b = __builtin_convertvector(v, bf16x2_t); return __builtin_bit_cast(unsigned, b); }
; __device__ __forceinline__ float lo16(unsigned u) { return __uint_as_float(u << 16); }
; __device__ __forceinline__ float hi16(unsigned u) { return __uint_as_float(u & 0xffff0000u); }
; __device__ __forceinline__ float silu_fast(float v) { return v * __builtin_amdgcn_rcpf(1.f + __builtin_amdgcn_exp2f(-v * LOG2E)); }
; __device__ __forceinline__ float lo16(unsigned u) { return __uint_as_float(u << 16); }
; template <class Put>
; __device__ __forceinline__ void conv_compute(const ConvRaw& R, const float* cw, const float* cb, int col0, int rg, const Put& put) {
;     const f32x4 w0a = *(const f32x4*)(cw + col0), w0b = *(const f32x4*)(cw + col0 + 4), w1a = *(const f32x4*)(cw + XBCW + col0), w1b = *(const f32x4*)(cw + XBCW + col0 + 4);
;     const f32x4 w2a = *(const f32x4*)(cw + 2 * XBCW + col0), w2b = *(const f32x4*)(cw + 2 * XBCW + col0 + 4), ba = *(const f32x4*)(cb + col0), bb = *(const f32x4*)(cb + col0 + 4);
;     const int r0 = 8 * rg;
; #pragma unroll
;     for (int rr = 0; rr < 8; ++rr) {
;         const u32x4 xm = R.r[rr], x0 = R.r[rr + 1], xp = R.r[rr + 2]; u32x4 o;
; #pragma unroll
;         for (int e = 0; e < 4; ++e) {
;             const float wl0 = e < 2 ? w0a[2 * e] : w0b[2 * e - 4], wh0 = e < 2 ? w0a[2 * e + 1] : w0b[2 * e - 3];
;             const float wl1 = e < 2 ? w1a[2 * e] : w1b[2 * e - 4], wh1 = e < 2 ? w1a[2 * e + 1] : w1b[2 * e - 3];
;             const float wl2 = e < 2 ? w2a[2 * e] : w2b[2 * e - 4], wh2 = e < 2 ? w2a[2 * e + 1] : w2b[2 * e - 3];
;             const float bl = e < 2 ? ba[2 * e] : bb[2 * e - 4], bh = e < 2 ? ba[2 * e + 1] : bb[2 * e - 3];
;             const float vl = bl + wl0 * lo16(xm[e]) + wl1 * lo16(x0[e]) + wl2 * lo16(xp[e]);
;             const float vh = bh + wh0 * hi16(xm[e]) + wh1 * hi16(x0[e]) + wh2 * hi16(xp[e]);
;             o[e] = cvtpk(silu_fast(vl), silu_fast(vh));
;         }
;         put(r0 + rr, o);
;     }
; }
; template <class Wait>
; __device__ __forceinline__ void out_unit(Frame& F, const Ptrs& P, int b, int c, int g, const Wait& wait) {
;     ...
;     conv_compute(R2, P.conv_w, P.conv_b, col2, rg2, PutTr{lds + L_XS + hl2 * 16384, ch2});
	v_pk_mul_f32 v[78:79], v[78:79], v[84:85]
	s_nop 0
	v_cvt_pk_bf16_f32 v71, v78, v79
	ds_write_b128 v75, v[68:71]
	v_lshlrev_b32_e32 v70, 16, v52
	v_and_b32_e32 v71, 0xffff0000, v52
	v_pk_fma_f32 v[66:67], v[24:25], v[70:71], v[66:67]
	s_nop 0
	v_mul_f32_e32 v52, 0xbfb8aa3b, v66
	v_exp_f32_e32 v52, v52
	s_nop 0
	v_add_f32_e32 v52, 1.0, v52
	v_rcp_f32_e32 v68, v52
	v_mul_f32_e32 v52, 0xbfb8aa3b, v67
	v_exp_f32_e32 v52, v52
	s_nop 0
	v_add_f32_e32 v52, 1.0, v52
	v_rcp_f32_e32 v69, v52
	s_nop 0
	v_pk_mul_f32 v[66:67], v[66:67], v[68:69]
	s_nop 0
	v_cvt_pk_bf16_f32 v78, v66, v67
	v_pk_fma_f32 v[66:67], v[18:19], v[80:81], v[30:31]
	v_lshlrev_b32_e32 v68, 16, v53
	v_pk_fma_f32 v[66:67], v[22:23], v[56:57], v[66:67]
	v_and_b32_e32 v69, 0xffff0000, v53
	v_pk_fma_f32 v[52:53], v[26:27], v[68:69], v[66:67]
	v_pk_fma_f32 v[56:57], v[18:19], v[56:57], v[30:31]
	v_mul_f32_e32 v66, 0xbfb8aa3b, v52
	v_mul_f32_e32 v67, 0xbfb8aa3b, v53
	v_exp_f32_e32 v66, v66
	v_exp_f32_e32 v67, v67
	v_pk_fma_f32 v[56:57], v[22:23], v[68:69], v[56:57]
	v_add_f32_e32 v66, 1.0, v66
	v_add_f32_e32 v67, 1.0, v67
	v_rcp_f32_e32 v66, v66
	v_rcp_f32_e32 v67, v67
	s_nop 0
	v_pk_mul_f32 v[52:53], v[52:53], v[66:67]
	s_nop 0
	v_cvt_pk_bf16_f32 v79, v52, v53
	v_pk_fma_f32 v[52:53], v[0:1], v[82:83], v[12:13]
	v_lshlrev_b32_e32 v66, 16, v54
	v_pk_fma_f32 v[52:53], v[8:9], v[60:61], v[52:53]
	v_and_b32_e32 v67, 0xffff0000, v54
	v_pk_fma_f32 v[52:53], v[4:5], v[66:67], v[52:53]
	s_nop 0
	v_mul_f32_e32 v54, 0xbfb8aa3b, v52
	v_exp_f32_e32 v54, v54
	s_nop 0
	v_add_f32_e32 v54, 1.0, v54
	v_rcp_f32_e32 v80, v54
	v_mul_f32_e32 v54, 0xbfb8aa3b, v53
	v_exp_f32_e32 v54, v54
	s_nop 0
	v_add_f32_e32 v54, 1.0, v54
	v_rcp_f32_e32 v81, v54
	s_nop 0
	v_pk_mul_f32 v[52:53], v[52:53], v[80:81]
	s_nop 0
	v_cvt_pk_bf16_f32 v80, v52, v53
	v_pk_fma_f32 v[52:53], v[2:3], v[62:63], v[14:15]
	s_nop 0
	v_pk_fma_f32 v[62:63], v[10:11], v[58:59], v[52:53]
	v_lshlrev_b32_e32 v52, 16, v55
	v_and_b32_e32 v53, 0xffff0000, v55
	v_pk_fma_f32 v[54:55], v[6:7], v[52:53], v[62:63]
	v_pk_fma_f32 v[58:59], v[2:3], v[58:59], v[14:15]
	v_mul_f32_e32 v62, 0xbfb8aa3b, v54
	v_mul_f32_e32 v63, 0xbfb8aa3b, v55
	v_exp_f32_e32 v62, v62
	v_exp_f32_e32 v63, v63
	v_pk_fma_f32 v[58:59], v[10:11], v[52:53], v[58:59]
	v_add_f32_e32 v62, 1.0, v62
	v_add_f32_e32 v63, 1.0, v63
	v_rcp_f32_e32 v62, v62
	v_rcp_f32_e32 v63, v63
	s_nop 0
	v_pk_mul_f32 v[54:55], v[54:55], v[62:63]
	s_nop 0
	v_cvt_pk_bf16_f32 v81, v54, v55
	v_pk_fma_f32 v[54:55], v[16:17], v[64:65], v[28:29]
	v_lshlrev_b32_e32 v64, 16, v48
	v_pk_fma_f32 v[54:55], v[20:21], v[70:71], v[54:55]
	v_and_b32_e32 v65, 0xffff0000, v48
	v_pk_fma_f32 v[54:55], v[24:25], v[64:65], v[54:55]
	ds_write_b128 v75, v[78:81] offset:64
	v_mul_f32_e32 v48, 0xbfb8aa3b, v54
	v_exp_f32_e32 v48, v48
	s_nop 0
	v_add_f32_e32 v48, 1.0, v48
	v_rcp_f32_e32 v62, v48
	v_mul_f32_e32 v48, 0xbfb8aa3b, v55
	v_exp_f32_e32 v48, v48
	s_nop 0
	v_add_f32_e32 v48, 1.0, v48
	v_rcp_f32_e32 v63, v48
	v_lshlrev_b32_e32 v48, 16, v49
	v_and_b32_e32 v49, 0xffff0000, v49
	v_pk_fma_f32 v[56:57], v[26:27], v[48:49], v[56:57]
	v_pk_mul_f32 v[54:55], v[54:55], v[62:63]
	s_nop 0
	v_cvt_pk_bf16_f32 v54, v54, v55
	v_mul_f32_e32 v55, 0xbfb8aa3b, v56
	v_exp_f32_e32 v55, v55
	s_nop 0
	v_add_f32_e32 v55, 1.0, v55
	v_rcp_f32_e32 v62, v55
	v_mul_f32_e32 v55, 0xbfb8aa3b, v57
	v_exp_f32_e32 v55, v55
	s_nop 0
	v_add_f32_e32 v55, 1.0, v55
	v_rcp_f32_e32 v63, v55
	s_nop 0
	v_pk_mul_f32 v[56:57], v[56:57], v[62:63]
	s_nop 0
	v_cvt_pk_bf16_f32 v55, v56, v57
	v_pk_fma_f32 v[56:57], v[0:1], v[60:61], v[12:13]
	v_lshlrev_b32_e32 v62, 16, v50
	v_pk_fma_f32 v[56:57], v[8:9], v[66:67], v[56:57]
	v_and_b32_e32 v63, 0xffff0000, v50
	v_pk_fma_f32 v[56:57], v[4:5], v[62:63], v[56:57]
	s_nop 0
	v_mul_f32_e32 v50, 0xbfb8aa3b, v56
	v_exp_f32_e32 v50, v50
	s_nop 0
	v_add_f32_e32 v50, 1.0, v50
	v_rcp_f32_e32 v60, v50
	v_mul_f32_e32 v50, 0xbfb8aa3b, v57
	v_exp_f32_e32 v50, v50
	s_nop 0
	v_add_f32_e32 v50, 1.0, v50
	v_rcp_f32_e32 v61, v50
	s_nop 0
	v_pk_mul_f32 v[56:57], v[56:57], v[60:61]
	v_lshlrev_b32_e32 v60, 16, v51
	v_and_b32_e32 v61, 0xffff0000, v51
	v_pk_fma_f32 v[50:51], v[6:7], v[60:61], v[58:59]
	v_cvt_pk_bf16_f32 v56, v56, v57
	v_mul_f32_e32 v57, 0xbfb8aa3b, v50
	v_exp_f32_e32 v57, v57
	s_nop 0
	v_add_f32_e32 v57, 1.0, v57
	v_rcp_f32_e32 v58, v57
	v_mul_f32_e32 v57, 0xbfb8aa3b, v51
	v_exp_f32_e32 v57, v57
	s_nop 0
	v_add_f32_e32 v57, 1.0, v57
	v_rcp_f32_e32 v59, v57
	s_nop 0
	v_pk_mul_f32 v[50:51], v[50:51], v[58:59]
	s_nop 0
	v_cvt_pk_bf16_f32 v57, v50, v51
	v_pk_fma_f32 v[50:51], v[16:17], v[70:71], v[28:29]
	v_lshlrev_b32_e32 v58, 16, v44
	v_pk_fma_f32 v[50:51], v[20:21], v[64:65], v[50:51]
	v_and_b32_e32 v59, 0xffff0000, v44
	v_pk_fma_f32 v[50:51], v[24:25], v[58:59], v[50:51]
	ds_write_b128 v75, v[54:57] offset:128
	v_mul_f32_e32 v44, 0xbfb8aa3b, v50
	v_exp_f32_e32 v44, v44
	v_lshlrev_b32_e32 v56, 16, v45
	v_and_b32_e32 v57, 0xffff0000, v45
	v_add_f32_e32 v44, 1.0, v44
	v_rcp_f32_e32 v54, v44
	v_mul_f32_e32 v44, 0xbfb8aa3b, v51
	v_exp_f32_e32 v44, v44
	s_nop 0
	v_add_f32_e32 v44, 1.0, v44
	v_rcp_f32_e32 v55, v44
	s_nop 0
	v_pk_mul_f32 v[50:51], v[50:51], v[54:55]
	s_nop 0
	v_cvt_pk_bf16_f32 v44, v50, v51
	v_pk_fma_f32 v[50:51], v[18:19], v[68:69], v[30:31]
	s_nop 0
	v_pk_fma_f32 v[50:51], v[22:23], v[48:49], v[50:51]
	s_nop 0
	v_pk_fma_f32 v[50:51], v[26:27], v[56:57], v[50:51]
	s_nop 0
	v_mul_f32_e32 v45, 0xbfb8aa3b, v50
	v_exp_f32_e32 v45, v45
	s_nop 0
	v_add_f32_e32 v45, 1.0, v45
	v_rcp_f32_e32 v54, v45
	v_mul_f32_e32 v45, 0xbfb8aa3b, v51
	v_exp_f32_e32 v45, v45
	s_nop 0
	v_add_f32_e32 v45, 1.0, v45
	v_rcp_f32_e32 v55, v45
	s_nop 0
; __device__ __forceinline__ unsigned cvtpk(float lo, float hi) { f32x2_t v = {lo, hi}; bf16x2_t b = __builtin_convertvector(v, bf16x2_t); return __builtin_bit_cast(unsigned, b); }
; __device__ __forceinline__ float lo16(unsigned u) { return __uint_as_float(u << 16); }
; __device__ __forceinline__ float hi16(unsigned u) { return __uint_as_float(u & 0xffff0000u); }
; __device__ __forceinline__ float silu_fast(float v) { return v * __builtin_amdgcn_rcpf(1.f + __builtin_amdgcn_exp2f(-v * LOG2E)); }
; __device__ __forceinline__ float lo16(unsigned u) { return __uint_as_float(u << 16); }
; template <class Put>
; __device__ __forceinline__ void conv_compute(const ConvRaw& R, const float* cw, const float* cb, int col0, int rg, const Put& put) {
;     const f32x4 w0a = *(const f32x4*)(cw + col0), w0b = *(const f32x4*)(cw + col0 + 4), w1a = *(const f32x4*)(cw + XBCW + col0), w1b = *(const f32x4*)(cw + XBCW + col0 + 4);
;     const f32x4 w2a = *(const f32x4*)(cw + 2 * XBCW + col0), w2b = *(const f32x4*)(cw + 2 * XBCW + col0 + 4), ba = *(const f32x4*)(cb + col0), bb = *(const f32x4*)(cb + col0 + 4);
;     const int r0 = 8 * rg;
; #pragma unroll
;     for (int rr = 0; rr < 8; ++rr) {
;         const u32x4 xm = R.r[rr], x0 = R.r[rr + 1], xp = R.r[rr + 2]; u32x4 o;
; #pragma unroll
;         for (int e = 0; e < 4; ++e) {
;             const float wl0 = e < 2 ? w0a[2 * e] : w0b[2 * e - 4], wh0 = e < 2 ? w0a[2 * e + 1] : w0b[2 * e - 3];
;             const float wl1 = e < 2 ? w1a[2 * e] : w1b[2 * e - 4], wh1 = e < 2 ? w1a[2 * e + 1] : w1b[2 * e - 3];
;             const float wl2 = e < 2 ? w2a[2 * e] : w2b[2 * e - 4], wh2 = e < 2 ? w2a[2 * e + 1] : w2b[2 * e - 3];
;             const float bl = e < 2 ? ba[2 * e] : bb[2 * e - 4], bh = e < 2 ? ba[2 * e + 1] : bb[2 * e - 3];
;             const float vl = bl + wl0 * lo16(xm[e]) + wl1 * lo16(x0[e]) + wl2 * lo16(xp[e]);
;             const float vh = bh + wh0 * hi16(xm[e]) + wh1 * hi16(x0[e]) + wh2 * hi16(xp[e]);
;             o[e] = cvtpk(silu_fast(vl), silu_fast(vh));
;         }
;         put(r0 + rr, o);
;     }
; }
; template <class Wait>
; __device__ __forceinline__ void out_unit(Frame& F, const Ptrs& P, int b, int c, int g, const Wait& wait) {
;     ...
;     conv_compute(R2, P.conv_w, P.conv_b, col2, rg2, PutTr{lds + L_XS + hl2 * 16384, ch2});
	v_pk_mul_f32 v[50:51], v[50:51], v[54:55]
	s_nop 0
	v_cvt_pk_bf16_f32 v45, v50, v51
	v_pk_fma_f32 v[50:51], v[0:1], v[66:67], v[12:13]
	v_lshlrev_b32_e32 v54, 16, v46
	v_pk_fma_f32 v[50:51], v[8:9], v[62:63], v[50:51]
	v_and_b32_e32 v55, 0xffff0000, v46
	v_pk_fma_f32 v[50:51], v[4:5], v[54:55], v[50:51]
	s_nop 0
	v_mul_f32_e32 v46, 0xbfb8aa3b, v50
	v_exp_f32_e32 v46, v46
	s_nop 0
	v_add_f32_e32 v46, 1.0, v46
	v_rcp_f32_e32 v66, v46
	v_mul_f32_e32 v46, 0xbfb8aa3b, v51
	v_exp_f32_e32 v46, v46
	s_nop 0
	v_add_f32_e32 v46, 1.0, v46
	v_rcp_f32_e32 v67, v46
	s_nop 0
	v_pk_mul_f32 v[50:51], v[50:51], v[66:67]
	s_nop 0
	v_cvt_pk_bf16_f32 v46, v50, v51
	v_pk_fma_f32 v[50:51], v[2:3], v[52:53], v[14:15]
	v_lshlrev_b32_e32 v52, 16, v47
	v_pk_fma_f32 v[50:51], v[10:11], v[60:61], v[50:51]
	v_and_b32_e32 v53, 0xffff0000, v47
	v_pk_fma_f32 v[50:51], v[6:7], v[52:53], v[50:51]
	s_nop 0
	v_mul_f32_e32 v47, 0xbfb8aa3b, v50
	v_exp_f32_e32 v47, v47
	s_nop 0
	v_add_f32_e32 v47, 1.0, v47
	v_rcp_f32_e32 v66, v47
	v_mul_f32_e32 v47, 0xbfb8aa3b, v51
	v_exp_f32_e32 v47, v47
	s_nop 0
	v_add_f32_e32 v47, 1.0, v47
	v_rcp_f32_e32 v67, v47
	s_nop 0
	v_pk_mul_f32 v[50:51], v[50:51], v[66:67]
	s_nop 0
	v_cvt_pk_bf16_f32 v47, v50, v51
	ds_write_b128 v75, v[44:47] offset:192
	v_pk_fma_f32 v[44:45], v[16:17], v[64:65], v[28:29]
	v_lshlrev_b32_e32 v50, 16, v40
	v_pk_fma_f32 v[44:45], v[20:21], v[58:59], v[44:45]
	v_and_b32_e32 v51, 0xffff0000, v40
	v_pk_fma_f32 v[44:45], v[24:25], v[50:51], v[44:45]
	s_nop 0
	v_mul_f32_e32 v40, 0xbfb8aa3b, v44
	v_exp_f32_e32 v40, v40
	s_nop 0
	v_add_f32_e32 v40, 1.0, v40
	v_rcp_f32_e32 v46, v40
	v_mul_f32_e32 v40, 0xbfb8aa3b, v45
	v_exp_f32_e32 v40, v40
	s_nop 0
	v_add_f32_e32 v40, 1.0, v40
	v_rcp_f32_e32 v47, v40
	s_nop 0
	v_pk_mul_f32 v[44:45], v[44:45], v[46:47]
	s_nop 0
	v_cvt_pk_bf16_f32 v40, v44, v45
	v_pk_fma_f32 v[44:45], v[18:19], v[48:49], v[30:31]
	v_lshlrev_b32_e32 v48, 16, v41
	v_pk_fma_f32 v[44:45], v[22:23], v[56:57], v[44:45]
	v_and_b32_e32 v49, 0xffff0000, v41
	v_pk_fma_f32 v[44:45], v[26:27], v[48:49], v[44:45]
	s_nop 0
	v_mul_f32_e32 v41, 0xbfb8aa3b, v44
	v_exp_f32_e32 v41, v41
	s_nop 0
	v_add_f32_e32 v41, 1.0, v41
	v_rcp_f32_e32 v46, v41
	v_mul_f32_e32 v41, 0xbfb8aa3b, v45
	v_exp_f32_e32 v41, v41
	s_nop 0
	v_add_f32_e32 v41, 1.0, v41
	v_rcp_f32_e32 v47, v41
	s_nop 0
	v_pk_mul_f32 v[44:45], v[44:45], v[46:47]
	s_nop 0
	v_cvt_pk_bf16_f32 v41, v44, v45
	v_pk_fma_f32 v[44:45], v[0:1], v[62:63], v[12:13]
	v_lshlrev_b32_e32 v46, 16, v42
	v_pk_fma_f32 v[44:45], v[8:9], v[54:55], v[44:45]
	v_and_b32_e32 v47, 0xffff0000, v42
	v_pk_fma_f32 v[44:45], v[4:5], v[46:47], v[44:45]
	s_nop 0
	v_mul_f32_e32 v42, 0xbfb8aa3b, v44
	v_exp_f32_e32 v42, v42
	s_nop 0
	v_add_f32_e32 v42, 1.0, v42
	v_rcp_f32_e32 v62, v42
	v_mul_f32_e32 v42, 0xbfb8aa3b, v45
	v_exp_f32_e32 v42, v42
	s_nop 0
	v_add_f32_e32 v42, 1.0, v42
	v_rcp_f32_e32 v63, v42
	s_nop 0
	v_pk_mul_f32 v[44:45], v[44:45], v[62:63]
	s_nop 0
	v_cvt_pk_bf16_f32 v42, v44, v45
	v_pk_fma_f32 v[44:45], v[2:3], v[60:61], v[14:15]
	s_nop 0
	v_pk_fma_f32 v[60:61], v[10:11], v[52:53], v[44:45]
	v_lshlrev_b32_e32 v44, 16, v43
	v_and_b32_e32 v45, 0xffff0000, v43
	v_pk_fma_f32 v[60:61], v[6:7], v[44:45], v[60:61]
	v_pk_fma_f32 v[52:53], v[2:3], v[52:53], v[14:15]
	v_mul_f32_e32 v43, 0xbfb8aa3b, v60
	v_exp_f32_e32 v43, v43
	v_pk_fma_f32 v[52:53], v[10:11], v[44:45], v[52:53]
	v_pk_fma_f32 v[44:45], v[2:3], v[44:45], v[14:15]
	v_add_f32_e32 v43, 1.0, v43
	v_rcp_f32_e32 v62, v43
	v_mul_f32_e32 v43, 0xbfb8aa3b, v61
	v_exp_f32_e32 v43, v43
	s_nop 0
	v_add_f32_e32 v43, 1.0, v43
	v_rcp_f32_e32 v63, v43
	s_nop 0
	v_pk_mul_f32 v[60:61], v[60:61], v[62:63]
	s_nop 0
	v_cvt_pk_bf16_f32 v43, v60, v61
	ds_write_b128 v75, v[40:43] offset:256
	v_pk_fma_f32 v[40:41], v[16:17], v[58:59], v[28:29]
	v_lshlrev_b32_e32 v42, 16, v36
	v_pk_fma_f32 v[40:41], v[20:21], v[50:51], v[40:41]
	v_and_b32_e32 v43, 0xffff0000, v36
	v_pk_fma_f32 v[40:41], v[24:25], v[42:43], v[40:41]
	v_pk_fma_f32 v[50:51], v[16:17], v[50:51], v[28:29]
	v_mul_f32_e32 v36, 0xbfb8aa3b, v40
	v_exp_f32_e32 v36, v36
	v_pk_fma_f32 v[50:51], v[20:21], v[42:43], v[50:51]
	v_pk_fma_f32 v[16:17], v[16:17], v[42:43], v[28:29]
	v_add_f32_e32 v36, 1.0, v36
	v_rcp_f32_e32 v58, v36
	v_mul_f32_e32 v36, 0xbfb8aa3b, v41
	v_exp_f32_e32 v36, v36
	s_nop 0
	v_add_f32_e32 v36, 1.0, v36
	v_rcp_f32_e32 v59, v36
	s_nop 0
	v_pk_mul_f32 v[40:41], v[40:41], v[58:59]
	s_nop 0
	v_cvt_pk_bf16_f32 v58, v40, v41
	v_pk_fma_f32 v[40:41], v[18:19], v[56:57], v[30:31]
	s_nop 0
	v_pk_fma_f32 v[56:57], v[22:23], v[48:49], v[40:41]
	v_lshlrev_b32_e32 v40, 16, v37
	v_and_b32_e32 v41, 0xffff0000, v37
	v_pk_fma_f32 v[36:37], v[26:27], v[40:41], v[56:57]
	v_pk_fma_f32 v[48:49], v[18:19], v[48:49], v[30:31]
	v_mul_f32_e32 v56, 0xbfb8aa3b, v36
	v_mul_f32_e32 v57, 0xbfb8aa3b, v37
	v_exp_f32_e32 v56, v56
	v_exp_f32_e32 v57, v57
	v_pk_fma_f32 v[48:49], v[22:23], v[40:41], v[48:49]
	v_pk_fma_f32 v[18:19], v[18:19], v[40:41], v[30:31]
	v_add_f32_e32 v56, 1.0, v56
	v_add_f32_e32 v57, 1.0, v57
	v_rcp_f32_e32 v56, v56
	v_rcp_f32_e32 v57, v57
	s_nop 0
	v_pk_mul_f32 v[36:37], v[36:37], v[56:57]
	s_nop 0
	v_cvt_pk_bf16_f32 v59, v36, v37
	v_pk_fma_f32 v[36:37], v[0:1], v[54:55], v[12:13]
	s_nop 0
	v_pk_fma_f32 v[54:55], v[8:9], v[46:47], v[36:37]
	v_lshlrev_b32_e32 v36, 16, v38
	v_and_b32_e32 v37, 0xffff0000, v38
; __device__ __forceinline__ unsigned xb_ld(unsigned* p)              { return __hip_atomic_load(p, __ATOMIC_RELAXED, __HIP_MEMORY_SCOPE_AGENT); }
; #define XB_SPIN(cond, bar) do { unsigned _sp = 0; while (cond) { __builtin_amdgcn_s_sleep(1); \
;     if ((++_sp & 255u) == 0u) { if (xb_ld(&(bar)[XB_TMO])) break; if (_sp > XB_SPIN_CAP) { atomicAdd(&(bar)[XB_TMO], 1u); break; } } } } while (0)
; __device__ __forceinline__ bool xb_thread0(int wave) { return wave == 0 && hw_lane() == 0; }
; __device__ __forceinline__ void xcd_barrier_wait(const XcdBarrier& b) {
;     if (xb_thread0(b.wave)) {
;         const unsigned g = b.st[2];
;         XB_SPIN(xb_ld(&b.bar[XB_TOPGEN]) <= g, b.bar);
;         __builtin_amdgcn_fence(__ATOMIC_ACQUIRE, "agent");
;         asm volatile("s_waitcnt vmcnt(0)" ::: "memory");
;     }
;     __syncthreads();
; }
; template <class Put>
; __device__ __forceinline__ void conv_compute(const ConvRaw& R, const float* cw, const float* cb, int col0, int rg, const Put& put) {
;     const f32x4 w0a = *(const f32x4*)(cw + col0), w0b = *(const f32x4*)(cw + col0 + 4), w1a = *(const f32x4*)(cw + XBCW + col0), w1b = *(const f32x4*)(cw + XBCW + col0 + 4);
;     const f32x4 w2a = *(const f32x4*)(cw + 2 * XBCW + col0), w2b = *(const f32x4*)(cw + 2 * XBCW + col0 + 4), ba = *(const f32x4*)(cb + col0), bb = *(const f32x4*)(cb + col0 + 4);
;     const int r0 = 8 * rg;
; #pragma unroll
;     for (int rr = 0; rr < 8; ++rr) {
;         const u32x4 xm = R.r[rr], x0 = R.r[rr + 1], xp = R.r[rr + 2]; u32x4 o;
; #pragma unroll
;         for (int e = 0; e < 4; ++e) {
;             const float wl0 = e < 2 ? w0a[2 * e] : w0b[2 * e - 4], wh0 = e < 2 ? w0a[2 * e + 1] : w0b[2 * e - 3];
;             const float wl1 = e < 2 ? w1a[2 * e] : w1b[2 * e - 4], wh1 = e < 2 ? w1a[2 * e + 1] : w1b[2 * e - 3];
;             const float wl2 = e < 2 ? w2a[2 * e] : w2b[2 * e - 4], wh2 = e < 2 ? w2a[2 * e + 1] : w2b[2 * e - 3];
;             const float bl = e < 2 ? ba[2 * e] : bb[2 * e - 4], bh = e < 2 ? ba[2 * e + 1] : bb[2 * e - 3];
;             const float vl = bl + wl0 * lo16(xm[e]) + wl1 * lo16(x0[e]) + wl2 * lo16(xp[e]);
;             const float vh = bh + wh0 * hi16(xm[e]) + wh1 * hi16(x0[e]) + wh2 * hi16(xp[e]);
;             o[e] = cvtpk(silu_fast(vl), silu_fast(vh));
;         }
;         put(r0 + rr, o);
;     }
; }
	v_pk_fma_f32 v[54:55], v[4:5], v[36:37], v[54:55]
	v_pk_fma_f32 v[46:47], v[0:1], v[46:47], v[12:13]
	v_mul_f32_e32 v38, 0xbfb8aa3b, v54
	v_exp_f32_e32 v38, v38
	v_pk_fma_f32 v[46:47], v[8:9], v[36:37], v[46:47]
	v_pk_fma_f32 v[0:1], v[0:1], v[36:37], v[12:13]
	v_add_f32_e32 v38, 1.0, v38
	v_rcp_f32_e32 v56, v38
	v_mul_f32_e32 v38, 0xbfb8aa3b, v55
	v_exp_f32_e32 v38, v38
	s_nop 0
	v_add_f32_e32 v38, 1.0, v38
	v_rcp_f32_e32 v57, v38
	v_lshlrev_b32_e32 v38, 16, v39
	v_and_b32_e32 v39, 0xffff0000, v39
	v_pk_fma_f32 v[52:53], v[6:7], v[38:39], v[52:53]
	v_pk_mul_f32 v[54:55], v[54:55], v[56:57]
	v_pk_fma_f32 v[44:45], v[10:11], v[38:39], v[44:45]
	v_cvt_pk_bf16_f32 v60, v54, v55
	v_mul_f32_e32 v54, 0xbfb8aa3b, v52
	v_mul_f32_e32 v55, 0xbfb8aa3b, v53
	v_exp_f32_e32 v54, v54
	v_exp_f32_e32 v55, v55
	v_add_f32_e32 v54, 1.0, v54
	v_add_f32_e32 v55, 1.0, v55
	v_rcp_f32_e32 v54, v54
	v_rcp_f32_e32 v55, v55
	s_nop 0
	v_pk_mul_f32 v[52:53], v[52:53], v[54:55]
	s_nop 0
	v_cvt_pk_bf16_f32 v61, v52, v53
	v_lshlrev_b32_e32 v52, 16, v32
	v_and_b32_e32 v53, 0xffff0000, v32
	v_pk_fma_f32 v[50:51], v[24:25], v[52:53], v[50:51]
	v_pk_fma_f32 v[16:17], v[20:21], v[52:53], v[16:17]
	v_mul_f32_e32 v32, 0xbfb8aa3b, v50
	v_exp_f32_e32 v32, v32
	ds_write_b128 v75, v[58:61] offset:320
	v_add_f32_e32 v32, 1.0, v32
	v_rcp_f32_e32 v54, v32
	v_mul_f32_e32 v32, 0xbfb8aa3b, v51
	v_exp_f32_e32 v32, v32
	s_nop 0
	v_add_f32_e32 v32, 1.0, v32
	v_rcp_f32_e32 v55, v32
	s_nop 0
	v_pk_mul_f32 v[50:51], v[50:51], v[54:55]
	s_nop 0
	v_cvt_pk_bf16_f32 v32, v50, v51
	v_lshlrev_b32_e32 v50, 16, v33
	v_and_b32_e32 v51, 0xffff0000, v33
	v_pk_fma_f32 v[48:49], v[26:27], v[50:51], v[48:49]
	v_pk_fma_f32 v[18:19], v[22:23], v[50:51], v[18:19]
	v_mul_f32_e32 v33, 0xbfb8aa3b, v48
	v_exp_f32_e32 v33, v33
	s_nop 0
	v_add_f32_e32 v33, 1.0, v33
	v_rcp_f32_e32 v54, v33
	v_mul_f32_e32 v33, 0xbfb8aa3b, v49
	v_exp_f32_e32 v33, v33
	s_nop 0
	v_add_f32_e32 v33, 1.0, v33
	v_rcp_f32_e32 v55, v33
	s_nop 0
	v_pk_mul_f32 v[48:49], v[48:49], v[54:55]
	s_nop 0
	v_cvt_pk_bf16_f32 v33, v48, v49
	v_lshlrev_b32_e32 v48, 16, v34
	v_and_b32_e32 v49, 0xffff0000, v34
	v_pk_fma_f32 v[46:47], v[4:5], v[48:49], v[46:47]
	v_pk_fma_f32 v[0:1], v[8:9], v[48:49], v[0:1]
	v_mul_f32_e32 v34, 0xbfb8aa3b, v46
	v_exp_f32_e32 v34, v34
	s_nop 0
	v_add_f32_e32 v34, 1.0, v34
	v_rcp_f32_e32 v54, v34
	v_mul_f32_e32 v34, 0xbfb8aa3b, v47
	v_exp_f32_e32 v34, v34
	s_nop 0
	v_add_f32_e32 v34, 1.0, v34
	v_rcp_f32_e32 v55, v34
	s_nop 0
	v_pk_mul_f32 v[46:47], v[46:47], v[54:55]
	s_nop 0
	v_cvt_pk_bf16_f32 v34, v46, v47
	v_lshlrev_b32_e32 v46, 16, v35
	v_and_b32_e32 v47, 0xffff0000, v35
	v_pk_fma_f32 v[44:45], v[6:7], v[46:47], v[44:45]
	s_nop 0
	v_mul_f32_e32 v35, 0xbfb8aa3b, v44
	v_exp_f32_e32 v35, v35
	s_nop 0
	v_add_f32_e32 v35, 1.0, v35
	v_rcp_f32_e32 v54, v35
	v_mul_f32_e32 v35, 0xbfb8aa3b, v45
	v_exp_f32_e32 v35, v35
	s_nop 0
	v_add_f32_e32 v35, 1.0, v35
	v_rcp_f32_e32 v55, v35
	s_nop 0
	v_pk_mul_f32 v[44:45], v[44:45], v[54:55]
	s_nop 0
	v_cvt_pk_bf16_f32 v35, v44, v45
	ds_write_b128 v75, v[32:35] offset:384
	v_lshlrev_b32_e32 v32, 16, v76
	v_and_b32_e32 v33, 0xffff0000, v76
	v_pk_fma_f32 v[16:17], v[24:25], v[32:33], v[16:17]
	s_nop 0
	v_mul_f32_e32 v20, 0xbfb8aa3b, v16
	v_mul_f32_e32 v21, 0xbfb8aa3b, v17
	v_exp_f32_e32 v20, v20
	v_exp_f32_e32 v21, v21
	v_add_f32_e32 v20, 1.0, v20
	v_add_f32_e32 v21, 1.0, v21
	v_rcp_f32_e32 v20, v20
	v_rcp_f32_e32 v21, v21
	s_nop 0
	v_pk_mul_f32 v[16:17], v[16:17], v[20:21]
	v_lshlrev_b32_e32 v20, 16, v74
	v_and_b32_e32 v21, 0xffff0000, v74
	v_pk_fma_f32 v[18:19], v[26:27], v[20:21], v[18:19]
	v_cvt_pk_bf16_f32 v16, v16, v17
	v_mul_f32_e32 v17, 0xbfb8aa3b, v18
	v_exp_f32_e32 v17, v17
	s_nop 0
	v_add_f32_e32 v17, 1.0, v17
	v_rcp_f32_e32 v20, v17
	v_mul_f32_e32 v17, 0xbfb8aa3b, v19
	v_exp_f32_e32 v17, v17
	s_nop 0
	v_add_f32_e32 v17, 1.0, v17
	v_rcp_f32_e32 v21, v17
	s_nop 0
	v_pk_mul_f32 v[18:19], v[18:19], v[20:21]
	s_nop 0
	v_cvt_pk_bf16_f32 v17, v18, v19
	v_lshlrev_b32_e32 v18, 16, v73
	v_and_b32_e32 v19, 0xffff0000, v73
	v_pk_fma_f32 v[0:1], v[4:5], v[18:19], v[0:1]
	s_nop 0
	v_mul_f32_e32 v4, 0xbfb8aa3b, v0
	v_mul_f32_e32 v5, 0xbfb8aa3b, v1
	v_exp_f32_e32 v4, v4
	v_exp_f32_e32 v5, v5
	v_add_f32_e32 v4, 1.0, v4
	v_add_f32_e32 v5, 1.0, v5
	v_rcp_f32_e32 v4, v4
	v_rcp_f32_e32 v5, v5
	s_nop 0
	v_pk_mul_f32 v[0:1], v[0:1], v[4:5]
	s_nop 0
	v_cvt_pk_bf16_f32 v18, v0, v1
	v_pk_fma_f32 v[0:1], v[2:3], v[38:39], v[14:15]
	v_lshlrev_b32_e32 v2, 16, v72
	v_pk_fma_f32 v[0:1], v[10:11], v[46:47], v[0:1]
	v_and_b32_e32 v3, 0xffff0000, v72
	v_pk_fma_f32 v[0:1], v[6:7], v[2:3], v[0:1]
	s_nop 0
	v_mul_f32_e32 v2, 0xbfb8aa3b, v0
	v_mul_f32_e32 v3, 0xbfb8aa3b, v1
	v_exp_f32_e32 v2, v2
	v_exp_f32_e32 v3, v3
	v_add_f32_e32 v2, 1.0, v2
	v_add_f32_e32 v3, 1.0, v3
	v_rcp_f32_e32 v2, v2
	v_rcp_f32_e32 v3, v3
	s_nop 0
	v_pk_mul_f32 v[0:1], v[0:1], v[2:3]
	s_nop 0
	v_cvt_pk_bf16_f32 v19, v0, v1
	ds_write_b128 v75, v[16:19] offset:448
	s_cbranch_vccnz .LBB0_741
	v_mbcnt_lo_u32_b32 v0, -1, 0
	v_mbcnt_hi_u32_b32 v0, -1, v0
	s_nop 0
	v_cmp_eq_u32_e32 vcc, 0, v0
	s_and_saveexec_b64 s[0:1], vcc
	s_cbranch_execz .LBB0_740
	v_mov_b32_e32 v0, s33
	ds_read_b32 v0, v0
	global_load_dword v1, v201, s[38:39] sc1
	s_waitcnt vmcnt(0) lgkmcnt(0)
	v_cmp_gt_u32_e32 vcc, v1, v0
	s_cbranch_vccnz .LBB0_739
	s_mov_b32 s8, 1
	s_branch .LBB0_729

; #define LAS __attribute__((address_space(3)))
; template <class Wait>
; __device__ __forceinline__ void out_unit(Frame& F, const Ptrs& P, int b, int c, int g, const Wait& wait) {
;     ...
;     { const unsigned char* blk = SB + ((((size_t)b * 64 + c) * 2 + 0) * 16 + h) * 16384 + hi * 512 + r32 * 16;
; #pragma unroll
;       for (int pb = 0; pb < 2; ++pb)
; #pragma unroll
;           for (int ks = 0; ks < 8; ++ks) A0[pb][ks] = *(const bf16x8*)(blk + (pb * 8 + ks) * 1024); }
;     ...
;     const LAS float* Vf = (const LAS float*)(lds + L_VEC) + (hl * 2 + 0) * 512; const LAS float* Vb = (const LAS float*)(lds + L_VEC) + (hl * 2 + 1) * 512;
;     const LAS unsigned char* xsb = lds + L_XS + hl * 16384 + ((lane >> 4) & 1) * 32 + (lane & 3) * 8 + (4 * hi + ((lane & 15) >> 2)) * 64;
;     const int q0 = 64 * qh + r32, q1 = q0 + 32;
;     const LAS unsigned char* crow0 = lds + L_CIMG + q0 * 256; const LAS unsigned char* crow1 = lds + L_CIMG + q1 * 256;
;     f32x16 y[2][2];
; #pragma unroll
;     for (int i = 0; i < 2; ++i)
; #pragma unroll
;         for (int j = 0; j < 2; ++j) y[i][j] = f32x16{};
; #pragma unroll
;     for (int ks = 0; ks < 8; ++ks) { const int chn = 2 * ks + hi;
;         const bf16x8 c0 = *(const LAS bf16x8*)(crow0 + ((chn ^ (q0 & 15)) * 16)), c1 = *(const LAS bf16x8*)(crow1 + ((chn ^ (q1 & 15)) * 16));
;         y[0][0] = __builtin_amdgcn_mfma_f32_32x32x16_bf16(A0[0][ks], c0, y[0][0], 0, 0, 0); y[0][1] = __builtin_amdgcn_mfma_f32_32x32x16_bf16(A0[0][ks], c1, y[0][1], 0, 0, 0);
;         y[1][0] = __builtin_amdgcn_mfma_f32_32x32x16_bf16(A0[1][ks], c0, y[1][0], 0, 0, 0); y[1][1] = __builtin_amdgcn_mfma_f32_32x32x16_bf16(A0[1][ks], c1, y[1][1], 0, 0, 0); }
.LBB0_741:
	s_add_u32 s0, s50, s18
	s_addc_u32 s1, s51, 0
	s_lshl_b64 s[0:1], s[0:1], 14
	s_add_u32 s0, s58, s0
	s_addc_u32 s1, s59, s1
	v_lshl_add_u64 v[0:1], s[0:1], 0, v[200:201]
	v_mov_b32_e32 v129, v201
	v_lshl_add_u64 v[4:5], v[0:1], 0, v[128:129]
	v_add_co_u32_e32 v6, vcc, s88, v4
	s_waitcnt lgkmcnt(0)
	s_nop 0
	v_addc_co_u32_e32 v7, vcc, 0, v5, vcc
	s_barrier
	global_load_dwordx4 v[0:3], v[4:5], off nt
	global_load_dwordx4 v[108:111], v[4:5], off offset:1024 nt
	global_load_dwordx4 v[96:99], v[4:5], off offset:2048 nt
	global_load_dwordx4 v[84:87], v[4:5], off offset:3072 nt
	global_load_dwordx4 v[88:91], v[6:7], off nt
	global_load_dwordx4 v[76:79], v[6:7], off offset:1024 nt
	global_load_dwordx4 v[68:71], v[6:7], off offset:2048 nt
	global_load_dwordx4 v[64:67], v[6:7], off offset:3072 nt
	v_add_co_u32_e32 v6, vcc, 0x2000, v4
	s_nop 1
	v_addc_co_u32_e32 v7, vcc, 0, v5, vcc
	v_add_co_u32_e32 v4, vcc, 0x3000, v4
	global_load_dwordx4 v[16:19], v[6:7], off nt
	global_load_dwordx4 v[116:119], v[6:7], off offset:1024 nt
	global_load_dwordx4 v[112:115], v[6:7], off offset:2048 nt
	global_load_dwordx4 v[104:107], v[6:7], off offset:3072 nt
	v_addc_co_u32_e32 v5, vcc, 0, v5, vcc
	global_load_dwordx4 v[100:103], v[4:5], off nt
	global_load_dwordx4 v[92:95], v[4:5], off offset:1024 nt
	global_load_dwordx4 v[80:83], v[4:5], off offset:2048 nt
	global_load_dwordx4 v[72:75], v[4:5], off offset:3072 nt
.LBB0_742:
	v_add_u32_e32 v121, 0, v121
	v_add_u32_e32 v122, 0, v122
	v_add_u32_e32 v225, v121, v123
	v_add_u32_e32 v226, v122, v123
	ds_read_b128 v[20:23], v225
	ds_read_b128 v[24:27], v226
	v_add_u32_e32 v227, v121, v124
	s_waitcnt vmcnt(15) lgkmcnt(1)
	v_mfma_f32_32x32x16_bf16 v[48:63], v[0:3], v[20:23], 0
	v_add_u32_e32 v228, v122, v124
	ds_read_b128 v[136:139], v227
	ds_read_b128 v[140:143], v228
	v_add_u32_e32 v229, v121, v125
	v_add_u32_e32 v230, v122, v125
	v_add_u32_e32 v231, v121, v126
	v_add_u32_e32 v232, v122, v126
	s_waitcnt lgkmcnt(2)
	v_mfma_f32_32x32x16_bf16 v[0:15], v[0:3], v[24:27], 0
	v_add_u32_e32 v233, v121, v127
	v_add_u32_e32 v234, v122, v127
	v_add_u32_e32 v235, v121, v133
	v_add_u32_e32 v236, v122, v133
	v_add_u32_e32 v237, v121, v134
	v_add_u32_e32 v238, v122, v134
	v_add_u32_e32 v239, v121, v135
	s_waitcnt vmcnt(7)
	v_mfma_f32_32x32x16_bf16 v[32:47], v[16:19], v[20:23], 0
	v_add_u32_e32 v240, v122, v135
	s_mov_b32 s2, 1
	v_mfma_f32_32x32x16_bf16 v[16:31], v[16:19], v[24:27], 0
	s_waitcnt lgkmcnt(1)
	v_mfma_f32_32x32x16_bf16 v[48:63], v[108:111], v[136:139], v[48:63]
	s_waitcnt lgkmcnt(0)
	v_mfma_f32_32x32x16_bf16 v[0:15], v[108:111], v[140:143], v[0:15]
	ds_read_b128 v[108:111], v229
	s_waitcnt vmcnt(6)
	v_mfma_f32_32x32x16_bf16 v[32:47], v[116:119], v[136:139], v[32:47]
	v_mfma_f32_32x32x16_bf16 v[16:31], v[116:119], v[140:143], v[16:31]
	ds_read_b128 v[116:119], v230
	s_waitcnt lgkmcnt(1)
	v_mfma_f32_32x32x16_bf16 v[48:63], v[96:99], v[108:111], v[48:63]
	s_waitcnt lgkmcnt(0)
	v_mfma_f32_32x32x16_bf16 v[0:15], v[96:99], v[116:119], v[0:15]
	ds_read_b128 v[96:99], v231
	s_waitcnt vmcnt(5)
	v_mfma_f32_32x32x16_bf16 v[32:47], v[112:115], v[108:111], v[32:47]
	ds_read_b128 v[108:111], v232
	v_mfma_f32_32x32x16_bf16 v[16:31], v[112:115], v[116:119], v[16:31]
	s_waitcnt lgkmcnt(1)
	v_mfma_f32_32x32x16_bf16 v[48:63], v[84:87], v[96:99], v[48:63]
	s_waitcnt lgkmcnt(0)
	v_mfma_f32_32x32x16_bf16 v[0:15], v[84:87], v[108:111], v[0:15]
	ds_read_b128 v[84:87], v233
	s_waitcnt vmcnt(4)
	v_mfma_f32_32x32x16_bf16 v[32:47], v[104:107], v[96:99], v[32:47]
	ds_read_b128 v[96:99], v234
	v_mfma_f32_32x32x16_bf16 v[16:31], v[104:107], v[108:111], v[16:31]
	v_lshlrev_b32_e32 v106, 2, v223
	s_waitcnt lgkmcnt(1)
	v_mfma_f32_32x32x16_bf16 v[48:63], v[88:91], v[84:87], v[48:63]
	s_waitcnt lgkmcnt(0)
	v_mfma_f32_32x32x16_bf16 v[0:15], v[88:91], v[96:99], v[0:15]
	ds_read_b128 v[88:91], v236
	s_waitcnt vmcnt(3)
	v_mfma_f32_32x32x16_bf16 v[32:47], v[100:103], v[84:87], v[32:47]
	ds_read_b128 v[84:87], v235
	v_mfma_f32_32x32x16_bf16 v[16:31], v[100:103], v[96:99], v[16:31]
	s_waitcnt lgkmcnt(0)
	v_mfma_f32_32x32x16_bf16 v[48:63], v[76:79], v[84:87], v[48:63]
	v_mfma_f32_32x32x16_bf16 v[0:15], v[76:79], v[88:91], v[0:15]
	ds_read_b128 v[76:79], v237
	s_waitcnt vmcnt(2)
	v_mfma_f32_32x32x16_bf16 v[32:47], v[92:95], v[84:87], v[32:47]
	ds_read_b128 v[84:87], v238
	v_mfma_f32_32x32x16_bf16 v[16:31], v[92:95], v[88:91], v[16:31]
	s_waitcnt lgkmcnt(1)
	v_mfma_f32_32x32x16_bf16 v[48:63], v[68:71], v[76:79], v[48:63]
	s_waitcnt lgkmcnt(0)
	v_mfma_f32_32x32x16_bf16 v[0:15], v[68:71], v[84:87], v[0:15]
	ds_read_b128 v[68:71], v239
	s_waitcnt vmcnt(1)
; #define LAS __attribute__((address_space(3)))
; #define SSD_SBAR() __builtin_amdgcn_sched_barrier(0)
; template <class Wait>
; __device__ __forceinline__ void out_unit(Frame& F, const Ptrs& P, int b, int c, int g, const Wait& wait) {
;     ...
;     for (int ks = 0; ks < 8; ++ks) { const int chn = 2 * ks + hi;
;         const bf16x8 c0 = *(const LAS bf16x8*)(crow0 + ((chn ^ (q0 & 15)) * 16)), c1 = *(const LAS bf16x8*)(crow1 + ((chn ^ (q1 & 15)) * 16));
;         y[0][0] = __builtin_amdgcn_mfma_f32_32x32x16_bf16(A0[0][ks], c0, y[0][0], 0, 0, 0); y[0][1] = __builtin_amdgcn_mfma_f32_32x32x16_bf16(A0[0][ks], c1, y[0][1], 0, 0, 0);
;         y[1][0] = __builtin_amdgcn_mfma_f32_32x32x16_bf16(A0[1][ks], c0, y[1][0], 0, 0, 0); y[1][1] = __builtin_amdgcn_mfma_f32_32x32x16_bf16(A0[1][ks], c1, y[1][1], 0, 0, 0); }
;     SSD_SBAR();
;     bf16x8 A1[2][8];
;     { const unsigned char* blk = SB + ((((size_t)b * 64 + c) * 2 + 1) * 16 + h) * 16384 + hi * 512 + r32 * 16;
; #pragma unroll
;       for (int pb = 0; pb < 2; ++pb)
; #pragma unroll
;           for (int ks = 0; ks < 8; ++ks) A1[pb][ks] = *(const bf16x8*)(blk + (pb * 8 + ks) * 1024); }
;     const size_t rowq0 = (size_t)b * SEQ + c * 128 + q0;
;     { const float e0 = __builtin_amdgcn_exp2f(Vf[q0]), e1 = __builtin_amdgcn_exp2f(Vf[q1]);
; #pragma unroll
;       for (int pb = 0; pb < 2; ++pb)
; #pragma unroll
;           for (int r = 0; r < 16; ++r) { y[pb][0][r] *= e0; y[pb][1][r] *= e1; } }
;     {
;         const float afq0 = Vf[q0], afq1 = Vf[q1], abq0 = Vb[q0], abq1 = Vb[q1];
; #pragma unroll 1
;         for (int ks = 0; ks < 8; ++ks) {
;             if (wid >= 4) { if (ks & 1) __builtin_amdgcn_s_setprio(0); else __builtin_amdgcn_s_setprio(1); }
;             const int sa = 16 * ks + 4 * hi, sb_ = sa + 8;
	v_mfma_f32_32x32x16_bf16 v[32:47], v[80:83], v[76:79], v[32:47]
	ds_read_b128 v[76:79], v240
	v_mfma_f32_32x32x16_bf16 v[16:31], v[80:83], v[84:87], v[16:31]
	s_waitcnt lgkmcnt(1)
	v_mfma_f32_32x32x16_bf16 v[48:63], v[64:67], v[68:71], v[48:63]
	s_waitcnt lgkmcnt(0)
	v_mfma_f32_32x32x16_bf16 v[0:15], v[64:67], v[76:79], v[0:15]
	v_lshlrev_b32_e32 v64, 1, v224
	v_and_b32_e32 v80, 32, v64
	v_lshlrev_b32_e32 v64, 3, v224
	v_and_b32_e32 v81, 24, v64
	s_waitcnt vmcnt(0)
	v_mfma_f32_32x32x16_bf16 v[32:47], v[72:75], v[68:71], v[32:47]
	v_mfma_f32_32x32x16_bf16 v[16:31], v[72:75], v[76:79], v[16:31]
	s_add_u32 s0, s95, s18
	s_addc_u32 s1, s34, 0
	s_lshl_b64 s[0:1], s[0:1], 14
	s_add_u32 s0, s58, s0
	s_addc_u32 s1, s59, s1
	v_lshl_add_u64 v[64:65], s[0:1], 0, v[200:201]
	v_lshl_add_u64 v[72:73], v[64:65], 0, v[128:129]
	v_add_co_u32_e32 v74, vcc, s88, v72
	global_load_dwordx4 v[64:67], v[72:73], off nt
	global_load_dwordx4 v[168:171], v[72:73], off offset:1024 nt
	global_load_dwordx4 v[156:159], v[72:73], off offset:2048 nt
	global_load_dwordx4 v[148:151], v[72:73], off offset:3072 nt
	v_addc_co_u32_e32 v75, vcc, 0, v73, vcc
	v_add_co_u32_e32 v76, vcc, s89, v72
	v_or_b32_e32 v104, s82, v222
	s_nop 0
	v_addc_co_u32_e32 v77, vcc, 0, v73, vcc
	global_load_dwordx4 v[144:147], v[74:75], off offset:1024 nt
	global_load_dwordx4 v[136:139], v[74:75], off offset:2048 nt
	global_load_dwordx4 v[164:167], v[76:77], off offset:-4096 nt
	global_load_dwordx4 v[68:71], v[76:77], off nt
	global_load_dwordx4 v[188:191], v[76:77], off offset:1024 nt
	global_load_dwordx4 v[184:187], v[76:77], off offset:2048 nt
	global_load_dwordx4 v[176:179], v[76:77], off offset:3072 nt
	v_add_co_u32_e32 v72, vcc, s90, v72
	s_mov_b32 s3, 0
	s_nop 0
	v_addc_co_u32_e32 v73, vcc, 0, v73, vcc
	global_load_dwordx4 v[140:143], v[74:75], off offset:3072 nt
	global_load_dwordx4 v[180:183], v[72:73], off nt
	global_load_dwordx4 v[172:175], v[72:73], off offset:1024 nt
	global_load_dwordx4 v[160:163], v[72:73], off offset:2048 nt
	global_load_dwordx4 v[152:155], v[72:73], off offset:3072 nt
	v_lshlrev_b32_e32 v73, 2, v202
	v_add_u32_e32 v72, s73, v73
	ds_read_b32 v128, v72
	v_lshlrev_b32_e32 v75, 2, v120
	v_add_u32_e32 v72, s73, v75
	ds_read_b32 v129, v72
	v_add_u32_e32 v242, s75, v73
	s_waitcnt lgkmcnt(1)
	v_exp_f32_e32 v72, v128
	v_add_u32_e32 v241, s75, v75
	ds_read_b32 v130, v242
	ds_read_b32 v131, v241
	s_waitcnt lgkmcnt(2)
	v_exp_f32_e32 v74, v129
	v_pk_mul_f32 v[62:63], v[62:63], v[72:73] op_sel_hi:[1,0]
	v_pk_mul_f32 v[60:61], v[60:61], v[72:73] op_sel_hi:[1,0]
	v_pk_mul_f32 v[58:59], v[58:59], v[72:73] op_sel_hi:[1,0]
	v_pk_mul_f32 v[56:57], v[56:57], v[72:73] op_sel_hi:[1,0]
	v_pk_mul_f32 v[54:55], v[54:55], v[72:73] op_sel_hi:[1,0]
	v_pk_mul_f32 v[52:53], v[52:53], v[72:73] op_sel_hi:[1,0]
	v_pk_mul_f32 v[50:51], v[50:51], v[72:73] op_sel_hi:[1,0]
	v_pk_mul_f32 v[48:49], v[48:49], v[72:73] op_sel_hi:[1,0]
	v_pk_mul_f32 v[46:47], v[46:47], v[72:73] op_sel_hi:[1,0]
	v_pk_mul_f32 v[44:45], v[44:45], v[72:73] op_sel_hi:[1,0]
	v_pk_mul_f32 v[42:43], v[42:43], v[72:73] op_sel_hi:[1,0]
	v_pk_mul_f32 v[40:41], v[40:41], v[72:73] op_sel_hi:[1,0]
	v_pk_mul_f32 v[38:39], v[38:39], v[72:73] op_sel_hi:[1,0]
	v_pk_mul_f32 v[36:37], v[36:37], v[72:73] op_sel_hi:[1,0]
	v_pk_mul_f32 v[34:35], v[34:35], v[72:73] op_sel_hi:[1,0]
	v_pk_mul_f32 v[32:33], v[32:33], v[72:73] op_sel_hi:[1,0]
	v_lshlrev_b32_e32 v72, 8, v104
	v_lshlrev_b32_e32 v73, 4, v224
	v_add3_u32 v134, 0, v72, v204
	v_lshlrev_b32_e32 v72, 8, v223
	v_and_b32_e32 v73, 0xc0, v73
	v_add3_u32 v72, s76, v72, v73
	v_add3_u32 v135, v72, v80, v81
	v_lshlrev_b32_e32 v72, 4, v223
	v_pk_mul_f32 v[14:15], v[14:15], v[74:75] op_sel_hi:[1,0]
	v_pk_mul_f32 v[12:13], v[12:13], v[74:75] op_sel_hi:[1,0]
	v_pk_mul_f32 v[10:11], v[10:11], v[74:75] op_sel_hi:[1,0]
	v_pk_mul_f32 v[8:9], v[8:9], v[74:75] op_sel_hi:[1,0]
	v_pk_mul_f32 v[6:7], v[6:7], v[74:75] op_sel_hi:[1,0]
	v_pk_mul_f32 v[4:5], v[4:5], v[74:75] op_sel_hi:[1,0]
	v_pk_mul_f32 v[2:3], v[2:3], v[74:75] op_sel_hi:[1,0]
	v_pk_mul_f32 v[0:1], v[0:1], v[74:75] op_sel_hi:[1,0]
	v_pk_mul_f32 v[30:31], v[30:31], v[74:75] op_sel_hi:[1,0]
	v_pk_mul_f32 v[28:29], v[28:29], v[74:75] op_sel_hi:[1,0]
	v_pk_mul_f32 v[26:27], v[26:27], v[74:75] op_sel_hi:[1,0]
	v_pk_mul_f32 v[24:25], v[24:25], v[74:75] op_sel_hi:[1,0]
	v_pk_mul_f32 v[22:23], v[22:23], v[74:75] op_sel_hi:[1,0]
	v_pk_mul_f32 v[20:21], v[20:21], v[74:75] op_sel_hi:[1,0]
	v_pk_mul_f32 v[18:19], v[18:19], v[74:75] op_sel_hi:[1,0]
	v_pk_mul_f32 v[16:17], v[16:17], v[74:75] op_sel_hi:[1,0]
	v_add_u32_e32 v133, v121, v204
	v_mov_b32_e32 v105, v104
	v_mov_b32_e32 v107, v202
	v_add_u32_e32 v192, s74, v72
	v_add_u32_e32 v193, s72, v72
	s_mov_b32 s4, 0
	s_branch .LBB0_744

; #define LAS __attribute__((address_space(3)))
; template <class Wait>
; __device__ __forceinline__ void out_unit(Frame& F, const Ptrs& P, int b, int c, int g, const Wait& wait) {
;     ...
;     u32x2 zv[2][2][4];
; #pragma unroll
;     for (int pb = 0; pb < 2; ++pb)
; #pragma unroll
;         for (int kk = 0; kk < 2; ++kk) { const u32x4 v = *(const u32x4*)(Z + rowq0 * 1024 + h * 64 + 32 * pb + 16 * kk + 8 * hi);
;             auto r0 = __builtin_amdgcn_permlane32_swap(v.x, v.z, false, false); auto r1 = __builtin_amdgcn_permlane32_swap(v.y, v.w, false, false);
;             zv[0][pb][2 * kk].x = r0[0]; zv[0][pb][2 * kk + 1].x = r0[1]; zv[0][pb][2 * kk].y = r1[0]; zv[0][pb][2 * kk + 1].y = r1[1]; }
;     {
;         f32x16 acc[2][2];
; #pragma unroll
;         for (int i = 0; i < 2; ++i)
; #pragma unroll
;             for (int j = 0; j < 2; ++j) acc[i][j] = f32x16{};
; #pragma unroll
;         for (int ks = 0; ks < 8; ++ks) { const int chn = 2 * ks + hi;
;             const bf16x8 c0 = *(const LAS bf16x8*)(crow0 + ((chn ^ (q0 & 15)) * 16)), c1 = *(const LAS bf16x8*)(crow1 + ((chn ^ (q1 & 15)) * 16));
;             acc[0][0] = __builtin_amdgcn_mfma_f32_32x32x16_bf16(A1[0][ks], c0, acc[0][0], 0, 0, 0); acc[0][1] = __builtin_amdgcn_mfma_f32_32x32x16_bf16(A1[0][ks], c1, acc[0][1], 0, 0, 0);
;             acc[1][0] = __builtin_amdgcn_mfma_f32_32x32x16_bf16(A1[1][ks], c0, acc[1][0], 0, 0, 0); acc[1][1] = __builtin_amdgcn_mfma_f32_32x32x16_bf16(A1[1][ks], c1, acc[1][1], 0, 0, 0); }
;         const float e0 = __builtin_amdgcn_exp2f(Vb[q0]), e1 = __builtin_amdgcn_exp2f(Vb[q1]);
; #pragma unroll
;         for (int pb = 0; pb < 2; ++pb)
; #pragma unroll
;             for (int r = 0; r < 16; ++r) { y[pb][0][r] += acc[pb][0][r] * e0; y[pb][1][r] += acc[pb][1][r] * e1; }
;     }
;     {
;         const float Dk = P.dskip[h];
; #pragma unroll
;         for (int pb = 0; pb < 2; ++pb)
; #pragma unroll
;             for (int kk = 0; kk < 2; ++kk) { const u32x4 v = *(const u32x4*)(Z + (rowq0 + 32) * 1024 + h * 64 + 32 * pb + 16 * kk + 8 * hi);
;                 auto r0 = __builtin_amdgcn_permlane32_swap(v.x, v.z, false, false); auto r1 = __builtin_amdgcn_permlane32_swap(v.y, v.w, false, false);
;                 zv[1][pb][2 * kk].x = r0[0]; zv[1][pb][2 * kk + 1].x = r0[1]; zv[1][pb][2 * kk].y = r1[0]; zv[1][pb][2 * kk + 1].y = r1[1]; }
.LBB0_765:
	v_or_b32_e32 v206, s44, v202
	v_mov_b32_e32 v207, s45
	v_lshlrev_b64 v[72:73], 11, v[206:207]
	v_lshl_add_u64 v[72:73], s[16:17], 0, v[72:73]
	s_lshl_b32 s0, s18, 7
	s_mov_b32 s1, s19
	v_mov_b32_e32 v205, v201
	v_lshl_add_u64 v[72:73], v[72:73], 0, s[0:1]
	v_lshlrev_b64 v[208:209], 1, v[204:205]
	v_lshl_add_u64 v[210:211], v[72:73], 0, v[208:209]
	global_load_dwordx4 v[196:199], v[210:211], off nt
	global_load_dwordx4 v[192:195], v[210:211], off offset:32 nt
	global_load_dwordx4 v[132:135], v[210:211], off offset:64 nt
	global_load_dwordx4 v[128:131], v[210:211], off offset:96 nt
	ds_read_b128 v[72:75], v225
	ds_read_b128 v[76:79], v226
	s_waitcnt vmcnt(19) lgkmcnt(1)
	v_mfma_f32_32x32x16_bf16 v[112:127], v[64:67], v[72:75], 0
	ds_read_b128 v[244:247], v227
	ds_read_b128 v[248:251], v228
	s_lshl_b64 s[2:3], s[18:19], 2
	s_add_u32 s2, s40, s2
	s_addc_u32 s3, s41, s3
	s_mov_b32 s1, 0x10000
	s_add_u32 s0, s10, s0
	s_waitcnt vmcnt(3)
	v_mov_b32_e32 v243, v198
	v_mfma_f32_32x32x16_bf16 v[96:111], v[68:71], v[72:75], 0
	v_mov_b32_e32 v205, v199
	s_waitcnt vmcnt(2)
	v_mov_b32_e32 v200, v194
	v_mov_b32_e32 v199, v195
	s_waitcnt vmcnt(1)
	v_mov_b32_e32 v198, v134
	v_mov_b32_e32 v195, v135
	s_waitcnt vmcnt(0)
	v_mov_b32_e32 v194, v130
	v_permlane32_swap_b32_e32 v196, v243
	s_waitcnt lgkmcnt(2)
	v_mfma_f32_32x32x16_bf16 v[80:95], v[64:67], v[76:79], 0
	v_permlane32_swap_b32_e32 v197, v205
	v_permlane32_swap_b32_e32 v129, v131
	v_permlane32_swap_b32_e32 v192, v200
	v_permlane32_swap_b32_e32 v193, v199
	v_mfma_f32_32x32x16_bf16 v[64:79], v[68:71], v[76:79], 0
	v_permlane32_swap_b32_e32 v132, v198
	v_permlane32_swap_b32_e32 v133, v195
	v_permlane32_swap_b32_e32 v128, v194
	s_waitcnt lgkmcnt(1)
	v_mfma_f32_32x32x16_bf16 v[112:127], v[168:171], v[244:247], v[112:127]
	v_mfma_f32_32x32x16_bf16 v[96:111], v[188:191], v[244:247], v[96:111]
	s_waitcnt lgkmcnt(0)
	v_mfma_f32_32x32x16_bf16 v[80:95], v[168:171], v[248:251], v[80:95]
	v_mfma_f32_32x32x16_bf16 v[64:79], v[188:191], v[248:251], v[64:79]
	ds_read_b128 v[168:171], v229
	ds_read_b128 v[188:191], v230
	s_waitcnt lgkmcnt(1)
	v_mfma_f32_32x32x16_bf16 v[112:127], v[156:159], v[168:171], v[112:127]
	v_mfma_f32_32x32x16_bf16 v[96:111], v[184:187], v[168:171], v[96:111]
	s_waitcnt lgkmcnt(0)
	v_mfma_f32_32x32x16_bf16 v[80:95], v[156:159], v[188:191], v[80:95]
	ds_read_b128 v[156:159], v231
	ds_read_b128 v[168:171], v232
	v_mfma_f32_32x32x16_bf16 v[64:79], v[184:187], v[188:191], v[64:79]
	s_waitcnt lgkmcnt(1)
	v_mfma_f32_32x32x16_bf16 v[112:127], v[148:151], v[156:159], v[112:127]
	v_mfma_f32_32x32x16_bf16 v[96:111], v[176:179], v[156:159], v[96:111]
	s_waitcnt lgkmcnt(0)
	v_mfma_f32_32x32x16_bf16 v[80:95], v[148:151], v[168:171], v[80:95]
	ds_read_b128 v[148:151], v233
	ds_read_b128 v[156:159], v234
	v_mfma_f32_32x32x16_bf16 v[64:79], v[176:179], v[168:171], v[64:79]
	s_waitcnt lgkmcnt(1)
	v_mfma_f32_32x32x16_bf16 v[112:127], v[164:167], v[148:151], v[112:127]
	v_mfma_f32_32x32x16_bf16 v[96:111], v[180:183], v[148:151], v[96:111]
	s_waitcnt lgkmcnt(0)
	v_mfma_f32_32x32x16_bf16 v[80:95], v[164:167], v[156:159], v[80:95]
	v_lshlrev_b32_e32 v164, 16, v196
	v_and_b32_e32 v165, 0xffff0000, v196
	v_mfma_f32_32x32x16_bf16 v[64:79], v[180:183], v[156:159], v[64:79]
	ds_read_b128 v[148:151], v235
	ds_read_b128 v[156:159], v236
	s_waitcnt lgkmcnt(1)
	v_mfma_f32_32x32x16_bf16 v[112:127], v[144:147], v[148:151], v[112:127]
	v_mfma_f32_32x32x16_bf16 v[96:111], v[172:175], v[148:151], v[96:111]
	s_waitcnt lgkmcnt(0)
	v_mfma_f32_32x32x16_bf16 v[80:95], v[144:147], v[156:159], v[80:95]
	ds_read_b128 v[144:147], v237
	ds_read_b128 v[148:151], v238
	v_mfma_f32_32x32x16_bf16 v[64:79], v[172:175], v[156:159], v[64:79]
	s_waitcnt lgkmcnt(1)
	v_mfma_f32_32x32x16_bf16 v[112:127], v[136:139], v[144:147], v[112:127]
	v_mfma_f32_32x32x16_bf16 v[96:111], v[160:163], v[144:147], v[96:111]
	s_waitcnt lgkmcnt(0)
	v_mfma_f32_32x32x16_bf16 v[80:95], v[136:139], v[148:151], v[80:95]
	ds_read_b128 v[134:137], v239
	ds_read_b128 v[144:147], v240
	ds_read_b32 v130, v242
	v_mfma_f32_32x32x16_bf16 v[64:79], v[160:163], v[148:151], v[64:79]
	ds_read_b32 v151, v241
	s_waitcnt lgkmcnt(1)
	v_exp_f32_e32 v150, v130
	global_load_dword v130, v201, s[2:3] nt
	s_mov_b64 s[2:3], 0x10000
	v_mfma_f32_32x32x16_bf16 v[112:127], v[140:143], v[134:137], v[112:127]
	v_mfma_f32_32x32x16_bf16 v[96:111], v[152:155], v[134:137], v[96:111]
	v_add_co_u32_e32 v136, vcc, s1, v210
	v_lshl_add_u64 v[134:135], v[210:211], 0, s[2:3]
	s_nop 0
	v_addc_co_u32_e32 v137, vcc, 0, v211, vcc
	s_waitcnt lgkmcnt(0)
	s_nop 5
	v_fma_f32 v48, v112, v150, v48
	v_fma_f32 v49, v113, v150, v49
	v_pk_fma_f32 v[50:51], v[114:115], v[150:151], v[50:51] op_sel_hi:[1,0,1]
	v_mfma_f32_32x32x16_bf16 v[80:95], v[140:143], v[144:147], v[80:95]
	global_load_dwordx4 v[138:141], v[134:135], off offset:64 nt
	v_fma_f32 v52, v116, v150, v52
	v_fma_f32 v53, v117, v150, v53
	v_fma_f32 v54, v118, v150, v54
	v_fma_f32 v55, v119, v150, v55
	s_addc_u32 s1, s11, 0
	v_pk_fma_f32 v[56:57], v[120:121], v[150:151], v[56:57] op_sel_hi:[1,0,1]
	v_pk_fma_f32 v[58:59], v[122:123], v[150:151], v[58:59] op_sel_hi:[1,0,1]
	v_pk_fma_f32 v[32:33], v[96:97], v[150:151], v[32:33] op_sel_hi:[1,0,1]
	v_mfma_f32_32x32x16_bf16 v[64:79], v[152:155], v[144:147], v[64:79]
	global_load_dwordx4 v[146:149], v[136:137], off nt
	global_load_dwordx4 v[142:145], v[134:135], off offset:32 nt
	v_fma_f32 v34, v98, v150, v34
	v_fma_f32 v35, v99, v150, v35
	global_load_dwordx4 v[134:137], v[134:135], off offset:96 nt
	v_pk_fma_f32 v[36:37], v[100:101], v[150:151], v[36:37] op_sel_hi:[1,0,1]
	v_pk_fma_f32 v[38:39], v[102:103], v[150:151], v[38:39] op_sel_hi:[1,0,1]
	v_pk_fma_f32 v[40:41], v[104:105], v[150:151], v[40:41] op_sel_hi:[1,0,1]
	v_pk_fma_f32 v[42:43], v[106:107], v[150:151], v[42:43] op_sel_hi:[1,0,1]
	v_cmp_eq_u32_e32 vcc, 0, v223
	s_waitcnt vmcnt(2)
; #define LAS __attribute__((address_space(3)))
; __device__ __forceinline__ unsigned cvtpk(float lo, float hi) { f32x2_t v = {lo, hi}; bf16x2_t b = __builtin_convertvector(v, bf16x2_t); return __builtin_bit_cast(unsigned, b); }
; __device__ __forceinline__ float lo16(unsigned u) { return __uint_as_float(u << 16); }
; __device__ __forceinline__ float hi16(unsigned u) { return __uint_as_float(u & 0xffff0000u); }
; __device__ __forceinline__ unsigned cvtpk(float lo, float hi) { f32x2_t v = {lo, hi}; bf16x2_t b = __builtin_convertvector(v, bf16x2_t); return __builtin_bit_cast(unsigned, b); }
; __device__ __forceinline__ float lo16(unsigned u) { return __uint_as_float(u << 16); }
; __device__ __forceinline__ float hi16(unsigned u) { return __uint_as_float(u & 0xffff0000u); }
; template <class Wait>
; __device__ __forceinline__ void out_unit(Frame& F, const Ptrs& P, int b, int c, int g, const Wait& wait) {
;     ...
; #pragma unroll
;         for (int qb = 0; qb < 2; ++qb) {
;             const int q = 64 * qh + 32 * qb + r32; const size_t row = rowq0 + 32 * qb; float ss = 0.f;
; #pragma unroll
;             for (int pb = 0; pb < 2; ++pb)
; #pragma unroll
;                 for (int kk = 0; kk < 2; ++kk) { u32x2 w[2];
; #pragma unroll
;                     for (int e = 0; e < 2; ++e) { const int g4 = 2 * kk + e, pc = 8 * g4 + 4 * hi;
;                         const u32x2 xv = *(const LAS u32x2*)(lds + L_XS + hl * 16384 + (pb * 8 + (q >> 4)) * 1024 + (q & 15) * 64 + pc * 2);
;                         const u32x2 zz = zv[qb][pb][g4];
;                         const float y0 = (y[pb][qb][4 * g4] + Dk * lo16(xv.x)) * lo16(zz.x), y1 = (y[pb][qb][4 * g4 + 1] + Dk * hi16(xv.x)) * hi16(zz.x);
;                         const float y2 = (y[pb][qb][4 * g4 + 2] + Dk * lo16(xv.y)) * lo16(zz.y), y3 = (y[pb][qb][4 * g4 + 3] + Dk * hi16(xv.y)) * hi16(zz.y);
;                         ss += (y0 * y0 + y1 * y1) + (y2 * y2 + y3 * y3);
;                         w[e].x = cvtpk(y0, y1); w[e].y = cvtpk(y2, y3); }
;                     auto r0 = __builtin_amdgcn_permlane32_swap(w[0].x, w[1].x, false, false); auto r1 = __builtin_amdgcn_permlane32_swap(w[0].y, w[1].y, false, false);
;                     *(u32x4*)(YG + row * 2048 + h * 64 + 32 * pb + 16 * kk + 8 * hi) = (u32x4){r0[0], r1[0], r0[1], r1[1]}; }
	v_mov_b32_e32 v154, v149
	v_mov_b32_e32 v149, v140
	v_lshlrev_b32_e32 v140, 6, v202
	s_waitcnt vmcnt(0)
	v_mov_b32_e32 v157, v136
	v_lshlrev_b32_e32 v136, 6, v224
	v_and_b32_e32 v136, 0x3c0, v136
	v_add3_u32 v158, s77, v136, v204
	v_and_b32_e32 v140, 0x1c00, v140
	v_add_u32_e32 v159, v158, v140
	ds_read2_b64 v[160:163], v159 offset1:2
	v_mov_b32_e32 v155, v148
	v_mov_b32_e32 v148, v141
	v_mov_b32_e32 v156, v137
	v_lshl_add_u64 v[136:137], s[0:1], 0, v[208:209]
	s_waitcnt lgkmcnt(0)
	v_lshlrev_b32_e32 v112, 16, v160
	v_and_b32_e32 v113, 0xffff0000, v160
	v_lshlrev_b32_e32 v114, 16, v161
	v_and_b32_e32 v115, 0xffff0000, v161
	v_pk_fma_f32 v[48:49], v[130:131], v[112:113], v[48:49] op_sel_hi:[0,1,1]
	v_lshlrev_b32_e32 v112, 16, v197
	v_and_b32_e32 v113, 0xffff0000, v197
	v_pk_fma_f32 v[50:51], v[130:131], v[114:115], v[50:51] op_sel_hi:[0,1,1]
	v_pk_mul_f32 v[48:49], v[48:49], v[164:165]
	v_pk_mul_f32 v[50:51], v[50:51], v[112:113]
	v_mul_f32_e32 v112, v49, v49
	v_mul_f32_e32 v114, v51, v51
	v_pk_fma_f32 v[112:113], v[48:49], v[48:49], v[112:113] op_sel_hi:[1,1,0]
	v_pk_fma_f32 v[114:115], v[50:51], v[50:51], v[114:115] op_sel_hi:[1,1,0]
	v_cvt_pk_bf16_f32 v48, v48, v49
	v_pk_add_f32 v[112:113], v[112:113], v[114:115]
	v_lshlrev_b32_e32 v114, 16, v162
	v_and_b32_e32 v115, 0xffff0000, v162
	v_cvt_pk_bf16_f32 v49, v50, v51
	v_lshlrev_b32_e32 v50, 16, v243
	v_and_b32_e32 v51, 0xffff0000, v243
	v_pk_fma_f32 v[52:53], v[130:131], v[114:115], v[52:53] op_sel_hi:[0,1,1]
	v_lshlrev_b32_e32 v114, 16, v163
	v_and_b32_e32 v115, 0xffff0000, v163
	v_pk_mul_f32 v[50:51], v[52:53], v[50:51]
	v_lshlrev_b32_e32 v52, 16, v205
	v_and_b32_e32 v53, 0xffff0000, v205
	v_pk_fma_f32 v[54:55], v[130:131], v[114:115], v[54:55] op_sel_hi:[0,1,1]
	v_pk_mul_f32 v[52:53], v[54:55], v[52:53]
	v_mul_f32_e32 v54, v51, v51
	v_lshlrev_b64 v[140:141], 12, v[206:207]
	v_pk_fma_f32 v[54:55], v[50:51], v[50:51], v[54:55] op_sel_hi:[1,1,0]
	v_cvt_pk_bf16_f32 v50, v50, v51
	v_cvt_pk_bf16_f32 v51, v52, v53
	v_mov_b32_e32 v153, v144
	v_mov_b32_e32 v152, v145
	v_lshl_add_u64 v[144:145], v[136:137], 0, v[140:141]
	v_permlane32_swap_b32_e32 v48, v50
	v_permlane32_swap_b32_e32 v49, v51
	global_store_dwordx4 v[144:145], v[48:51], off
	ds_read2_b64 v[48:51], v159 offset0:4 offset1:6
	v_mul_f32_e32 v114, v53, v53
	v_pk_fma_f32 v[114:115], v[52:53], v[52:53], v[114:115] op_sel_hi:[1,1,0]
	v_lshlrev_b32_e32 v52, 16, v192
	v_pk_add_f32 v[54:55], v[54:55], v[114:115]
	v_and_b32_e32 v53, 0xffff0000, v192
	v_pk_add_f32 v[54:55], v[112:113], v[54:55]
	s_waitcnt lgkmcnt(0)
	v_lshlrev_b32_e32 v112, 16, v48
	v_and_b32_e32 v113, 0xffff0000, v48
	v_pk_fma_f32 v[56:57], v[130:131], v[112:113], v[56:57] op_sel_hi:[0,1,1]
	v_lshlrev_b32_e32 v48, 16, v49
	v_and_b32_e32 v49, 0xffff0000, v49
	v_pk_mul_f32 v[52:53], v[56:57], v[52:53]
	v_lshlrev_b32_e32 v56, 16, v193
	v_and_b32_e32 v57, 0xffff0000, v193
	v_pk_fma_f32 v[48:49], v[130:131], v[48:49], v[58:59] op_sel_hi:[0,1,1]
	v_pk_mul_f32 v[56:57], v[48:49], v[56:57]
	v_mul_f32_e32 v48, v53, v53
	v_mul_f32_e32 v58, v57, v57
	v_pk_fma_f32 v[48:49], v[52:53], v[52:53], v[48:49] op_sel_hi:[1,1,0]
	v_pk_fma_f32 v[58:59], v[56:57], v[56:57], v[58:59] op_sel_hi:[1,1,0]
	s_lshl_b64 s[0:1], s[18:19], 16
	v_pk_add_f32 v[48:49], v[48:49], v[58:59]
	v_lshlrev_b32_e32 v58, 16, v50
	v_pk_add_f32 v[54:55], v[54:55], v[48:49]
	v_cvt_pk_bf16_f32 v49, v56, v57
	v_pk_fma_f32 v[56:57], v[124:125], v[150:151], v[60:61] op_sel_hi:[1,0,1]
	v_and_b32_e32 v59, 0xffff0000, v50
	v_cvt_pk_bf16_f32 v48, v52, v53
	v_lshlrev_b32_e32 v52, 16, v200
	v_and_b32_e32 v53, 0xffff0000, v200
	v_pk_fma_f32 v[56:57], v[130:131], v[58:59], v[56:57] op_sel_hi:[0,1,1]
	v_pk_fma_f32 v[58:59], v[126:127], v[150:151], v[62:63] op_sel_hi:[1,0,1]
	v_lshlrev_b32_e32 v50, 16, v51
	v_and_b32_e32 v51, 0xffff0000, v51
	v_pk_mul_f32 v[52:53], v[56:57], v[52:53]
	v_lshlrev_b32_e32 v56, 16, v199
	v_and_b32_e32 v57, 0xffff0000, v199
	v_pk_fma_f32 v[50:51], v[130:131], v[50:51], v[58:59] op_sel_hi:[0,1,1]
	v_pk_mul_f32 v[56:57], v[50:51], v[56:57]
	v_mul_f32_e32 v50, v53, v53
	v_mul_f32_e32 v58, v57, v57
	v_pk_fma_f32 v[50:51], v[52:53], v[52:53], v[50:51] op_sel_hi:[1,1,0]
	v_pk_fma_f32 v[58:59], v[56:57], v[56:57], v[58:59] op_sel_hi:[1,1,0]
	s_add_u32 s0, s61, s0
	v_pk_add_f32 v[50:51], v[50:51], v[58:59]
	v_add_u32_e32 v58, 0x2000, v159
	v_pk_add_f32 v[54:55], v[54:55], v[50:51]
	v_cvt_pk_bf16_f32 v50, v52, v53
	v_cvt_pk_bf16_f32 v51, v56, v57
	s_nop 0
	v_permlane32_swap_b32_e32 v48, v50
	v_permlane32_swap_b32_e32 v49, v51
	global_store_dwordx4 v[144:145], v[48:51], off offset:32
	ds_read2_b64 v[48:51], v58 offset1:2
	v_lshlrev_b32_e32 v52, 16, v132
	v_and_b32_e32 v53, 0xffff0000, v132
	s_addc_u32 s1, s62, s1
	v_permlane32_swap_b32_e32 v146, v155
	s_waitcnt lgkmcnt(0)
; #define LAS __attribute__((address_space(3)))
; __device__ __forceinline__ unsigned cvtpk(float lo, float hi) { f32x2_t v = {lo, hi}; bf16x2_t b = __builtin_convertvector(v, bf16x2_t); return __builtin_bit_cast(unsigned, b); }
; __device__ __forceinline__ float lo16(unsigned u) { return __uint_as_float(u << 16); }
; __device__ __forceinline__ float hi16(unsigned u) { return __uint_as_float(u & 0xffff0000u); }
; __device__ __forceinline__ unsigned cvtpk(float lo, float hi) { f32x2_t v = {lo, hi}; bf16x2_t b = __builtin_convertvector(v, bf16x2_t); return __builtin_bit_cast(unsigned, b); }
; __device__ __forceinline__ float lo16(unsigned u) { return __uint_as_float(u << 16); }
; __device__ __forceinline__ float hi16(unsigned u) { return __uint_as_float(u & 0xffff0000u); }
; template <class Wait>
; __device__ __forceinline__ void out_unit(Frame& F, const Ptrs& P, int b, int c, int g, const Wait& wait) {
;     ...
;                 for (int kk = 0; kk < 2; ++kk) { u32x2 w[2];
; #pragma unroll
;                     for (int e = 0; e < 2; ++e) { const int g4 = 2 * kk + e, pc = 8 * g4 + 4 * hi;
;                         const u32x2 xv = *(const LAS u32x2*)(lds + L_XS + hl * 16384 + (pb * 8 + (q >> 4)) * 1024 + (q & 15) * 64 + pc * 2);
;                         const u32x2 zz = zv[qb][pb][g4];
;                         const float y0 = (y[pb][qb][4 * g4] + Dk * lo16(xv.x)) * lo16(zz.x), y1 = (y[pb][qb][4 * g4 + 1] + Dk * hi16(xv.x)) * hi16(zz.x);
;                         const float y2 = (y[pb][qb][4 * g4 + 2] + Dk * lo16(xv.y)) * lo16(zz.y), y3 = (y[pb][qb][4 * g4 + 3] + Dk * hi16(xv.y)) * hi16(zz.y);
;                         ss += (y0 * y0 + y1 * y1) + (y2 * y2 + y3 * y3);
;                         w[e].x = cvtpk(y0, y1); w[e].y = cvtpk(y2, y3); }
;                     auto r0 = __builtin_amdgcn_permlane32_swap(w[0].x, w[1].x, false, false); auto r1 = __builtin_amdgcn_permlane32_swap(w[0].y, w[1].y, false, false);
;                     *(u32x4*)(YG + row * 2048 + h * 64 + 32 * pb + 16 * kk + 8 * hi) = (u32x4){r0[0], r1[0], r0[1], r1[1]}; }
;             { auto rr = __builtin_amdgcn_permlane32_swap(__float_as_uint(ss), __float_as_uint(ss), false, false); ss = __uint_as_float(rr[0]) + __uint_as_float(rr[1]); }
;             if (hi == 0) SSQ[(size_t)h * M + row] = ss;
	v_lshlrev_b32_e32 v56, 16, v48
	v_and_b32_e32 v57, 0xffff0000, v48
	v_pk_fma_f32 v[32:33], v[130:131], v[56:57], v[32:33] op_sel_hi:[0,1,1]
	v_lshlrev_b32_e32 v48, 16, v49
	v_and_b32_e32 v49, 0xffff0000, v49
	v_pk_mul_f32 v[32:33], v[32:33], v[52:53]
	v_lshlrev_b32_e32 v52, 16, v133
	v_and_b32_e32 v53, 0xffff0000, v133
	v_pk_fma_f32 v[34:35], v[130:131], v[48:49], v[34:35] op_sel_hi:[0,1,1]
	v_pk_mul_f32 v[34:35], v[34:35], v[52:53]
	v_mul_f32_e32 v48, v33, v33
	v_mul_f32_e32 v52, v35, v35
	v_pk_fma_f32 v[48:49], v[32:33], v[32:33], v[48:49] op_sel_hi:[1,1,0]
	v_pk_fma_f32 v[52:53], v[34:35], v[34:35], v[52:53] op_sel_hi:[1,1,0]
	v_cvt_pk_bf16_f32 v32, v32, v33
	v_pk_add_f32 v[48:49], v[48:49], v[52:53]
	v_lshlrev_b32_e32 v52, 16, v50
	v_and_b32_e32 v53, 0xffff0000, v50
	v_cvt_pk_bf16_f32 v33, v34, v35
	v_lshlrev_b32_e32 v34, 16, v198
	v_and_b32_e32 v35, 0xffff0000, v198
	v_pk_fma_f32 v[36:37], v[130:131], v[52:53], v[36:37] op_sel_hi:[0,1,1]
	v_lshlrev_b32_e32 v50, 16, v51
	v_and_b32_e32 v51, 0xffff0000, v51
	v_pk_mul_f32 v[34:35], v[36:37], v[34:35]
	v_lshlrev_b32_e32 v36, 16, v195
	v_and_b32_e32 v37, 0xffff0000, v195
	v_pk_fma_f32 v[38:39], v[130:131], v[50:51], v[38:39] op_sel_hi:[0,1,1]
	v_pk_mul_f32 v[36:37], v[38:39], v[36:37]
	v_mul_f32_e32 v38, v35, v35
	v_pk_fma_f32 v[38:39], v[34:35], v[34:35], v[38:39] op_sel_hi:[1,1,0]
	v_cvt_pk_bf16_f32 v34, v34, v35
	v_cvt_pk_bf16_f32 v35, v36, v37
	s_nop 0
	v_permlane32_swap_b32_e32 v32, v34
	v_permlane32_swap_b32_e32 v33, v35
	global_store_dwordx4 v[144:145], v[32:35], off offset:64
	ds_read2_b64 v[32:35], v58 offset0:4 offset1:6
	v_mul_f32_e32 v50, v37, v37
	v_pk_fma_f32 v[50:51], v[36:37], v[36:37], v[50:51] op_sel_hi:[1,1,0]
	v_pk_add_f32 v[48:49], v[54:55], v[48:49]
	v_pk_add_f32 v[38:39], v[38:39], v[50:51]
	v_lshlrev_b32_e32 v36, 16, v128
	v_pk_add_f32 v[38:39], v[48:49], v[38:39]
	s_waitcnt lgkmcnt(0)
	v_lshlrev_b32_e32 v48, 16, v32
	v_and_b32_e32 v49, 0xffff0000, v32
	v_and_b32_e32 v37, 0xffff0000, v128
	v_pk_fma_f32 v[40:41], v[130:131], v[48:49], v[40:41] op_sel_hi:[0,1,1]
	v_lshlrev_b32_e32 v32, 16, v33
	v_and_b32_e32 v33, 0xffff0000, v33
	v_pk_mul_f32 v[36:37], v[40:41], v[36:37]
	v_lshlrev_b32_e32 v40, 16, v129
	v_and_b32_e32 v41, 0xffff0000, v129
	v_pk_fma_f32 v[32:33], v[130:131], v[32:33], v[42:43] op_sel_hi:[0,1,1]
	v_pk_mul_f32 v[32:33], v[32:33], v[40:41]
	v_mul_f32_e32 v40, v37, v37
	v_mul_f32_e32 v42, v33, v33
	v_pk_fma_f32 v[40:41], v[36:37], v[36:37], v[40:41] op_sel_hi:[1,1,0]
	v_pk_fma_f32 v[42:43], v[32:33], v[32:33], v[42:43] op_sel_hi:[1,1,0]
	v_cvt_pk_bf16_f32 v36, v36, v37
	v_pk_add_f32 v[40:41], v[40:41], v[42:43]
	v_lshlrev_b32_e32 v42, 16, v34
	v_pk_add_f32 v[38:39], v[38:39], v[40:41]
	v_pk_fma_f32 v[40:41], v[108:109], v[150:151], v[44:45] op_sel_hi:[1,0,1]
	v_and_b32_e32 v43, 0xffff0000, v34
	v_cvt_pk_bf16_f32 v37, v32, v33
	v_lshlrev_b32_e32 v32, 16, v194
	v_and_b32_e32 v33, 0xffff0000, v194
	v_pk_fma_f32 v[40:41], v[130:131], v[42:43], v[40:41] op_sel_hi:[0,1,1]
	v_pk_fma_f32 v[42:43], v[110:111], v[150:151], v[46:47] op_sel_hi:[1,0,1]
	v_lshlrev_b32_e32 v34, 16, v35
	v_and_b32_e32 v35, 0xffff0000, v35
	v_pk_mul_f32 v[32:33], v[40:41], v[32:33]
	v_lshlrev_b32_e32 v40, 16, v131
	v_and_b32_e32 v41, 0xffff0000, v131
	v_pk_fma_f32 v[34:35], v[130:131], v[34:35], v[42:43] op_sel_hi:[0,1,1]
	v_pk_mul_f32 v[40:41], v[34:35], v[40:41]
	v_mul_f32_e32 v34, v33, v33
	v_mul_f32_e32 v42, v41, v41
	v_pk_fma_f32 v[34:35], v[32:33], v[32:33], v[34:35] op_sel_hi:[1,1,0]
	v_pk_fma_f32 v[42:43], v[40:41], v[40:41], v[42:43] op_sel_hi:[1,1,0]
	v_permlane32_swap_b32_e32 v147, v154
	v_pk_add_f32 v[34:35], v[34:35], v[42:43]
	v_permlane32_swap_b32_e32 v142, v153
	v_pk_add_f32 v[34:35], v[38:39], v[34:35]
	v_cvt_pk_bf16_f32 v38, v32, v33
	v_cvt_pk_bf16_f32 v39, v40, v41
	v_mov_b32_e32 v35, v34
	v_permlane32_swap_b32_e32 v143, v152
	v_permlane32_swap_b32_e32 v138, v149
	v_permlane32_swap_b32_e32 v139, v148
	v_permlane32_swap_b32_e32 v134, v157
	v_permlane32_swap_b32_e32 v135, v156
	v_permlane32_swap_b32_e32 v36, v38
	v_permlane32_swap_b32_e32 v37, v39
	v_permlane32_swap_b32_e32 v34, v35
	v_lshl_add_u64 v[32:33], v[206:207], 2, s[0:1]
	global_store_dwordx4 v[144:145], v[36:39], off offset:96
	s_and_saveexec_b64 s[0:1], vcc
	s_cbranch_execz .LBB0_767
	v_add_f32_e32 v34, v34, v35
	global_store_dword v[32:33], v34, off
